# v38 plus NA first-tile batched K/bias/V LDS reads, rwkvA next-task k_k/k_a and input prefetch kept in flight (no store drain), MLA tile loop: descriptor kept in SGPRs and first K fragments read above
# speedup vs baseline: 1.0088x; 1.0088x over previous
; __device__ __forceinline__ float sigmoidf_(float x) { return __builtin_amdgcn_rcpf(1.0f + __expf(-x)); }
; __device__ __forceinline__ void rwkvA_phase(const Frame& F, int l) {
;     ...
;         const int ch = head * 64 + F.lane;
;         const float kkc = F.in[I_KK][(size_t)l * AW + ch], kac = F.in[I_KA][(size_t)l * AW + ch];
;         {
;             float kk_[8], b_[8], kd_[8], r_[8], lw_[8], cl_[8];
;             float run = 0.f;
; #pragma unroll
;             for (int e = 0; e < 8; ++e) {
;                 const int i = F.wave * 8 + e;
;                 const float k = pk_[e], a = sigmoidf_(pza_[e]);
;                 lw_[e] = -0.6065306597126334f * sigmoidf_(pzw_[e]);
;                 r_[e] = pr_[e];
;                 const float kkr = k * kkc;
;                 const float nrm = sqrtf(wave_sum(kkr * kkr, F.lane));
;                 kk_[e] = kkr * __builtin_amdgcn_rcpf(fmaxf(nrm, 1e-12f));
.LBB0_750:
	s_mul_hi_i32 s0, s2, 0x3e0f83e1
	s_lshr_b32 s1, s0, 31
	s_ashr_i32 s0, s0, 5
	s_add_i32 s1, s0, s1
	s_lshl_b32 s0, s1, 5
	s_andn2_b32 s0, s0, 63
	v_add_u32_e32 v36, s0, v198
	v_readlane_b32 s34, v255, 14
	v_ashrrev_i32_e32 v37, 31, v36
	v_readlane_b32 s35, v255, 15
	s_mov_b64 s[94:95], s[74:75]
	s_mov_b64 s[8:9], s[72:73]
	v_mov_b32_e32 v129, v128
	v_lshl_add_u64 v[36:37], v[36:37], 0, s[34:35]
	v_readlane_b32 s60, v253, 42
	v_mov_b32_e32 v130, v128
	v_mov_b32_e32 v131, v128
	v_mov_b64_e32 v[0:1], v[128:129]
	v_lshlrev_b64 v[36:37], 2, v[36:37]
	v_readlane_b32 s74, v253, 56
	v_readlane_b32 s75, v253, 57
	v_mov_b64_e32 v[2:3], v[130:131]
	v_readlane_b32 s61, v253, 43
	v_lshl_add_u64 v[38:39], s[74:75], 0, v[36:37]
	s_nop 0
	v_readlane_b32 s62, v253, 44
	v_readlane_b32 s63, v253, 45
	v_readlane_b32 s64, v253, 46
	v_readlane_b32 s65, v253, 47
	v_readlane_b32 s66, v253, 48
	v_readlane_b32 s67, v253, 49
	v_readlane_b32 s68, v253, 50
	v_readlane_b32 s69, v253, 51
	v_readlane_b32 s70, v253, 52
	v_readlane_b32 s71, v253, 53
	v_readlane_b32 s72, v253, 54
	v_readlane_b32 s73, v253, 55
	v_readlane_b32 s60, v253, 58
	v_readlane_b32 s61, v253, 59
	v_readlane_b32 s62, v253, 60
	v_readlane_b32 s70, v254, 4
	v_lshl_add_u64 v[36:37], s[60:61], 0, v[36:37]
	s_nop 0
	v_readlane_b32 s71, v254, 5
	v_readlane_b32 s67, v254, 1
	v_readlane_b32 s34, v255, 4
	s_add_i32 s42, s2, s34
	s_cmp_ge_i32 s42, s85
	v_readlane_b32 s63, v253, 61
	v_readlane_b32 s64, v253, 62
	v_readlane_b32 s65, v253, 63
	v_readlane_b32 s66, v254, 0
	s_cselect_b64 s[34:35], -1, 0
	s_and_b64 vcc, exec, s[34:35]
	v_readlane_b32 s68, v254, 2
	v_readlane_b32 s69, v254, 3
	v_readlane_b32 s72, v254, 6
	v_readlane_b32 s73, v254, 7
	v_readlane_b32 s74, v254, 8
	v_readlane_b32 s75, v254, 9
	s_waitcnt vmcnt(28)
	v_mov_b32_e32 v44, v250
	v_mov_b32_e32 v36, v251
	v_mul_f32_e32 v43, v33, v44
	v_mul_f32_e32 v37, v43, v43
	v_mul_f32_e32 v42, v31, v44
	v_mul_f32_e32 v41, v30, v44
	v_mov_b32_dpp v37, v37 quad_perm:[1,0,3,2] row_mask:0xf bank_mask:0xf bound_ctrl:1
	v_fmac_f32_e32 v37, v43, v43
	v_mul_f32_e32 v40, v27, v44
	v_mul_f32_e32 v38, v26, v44
	v_add_f32_dpp v37, v37, v37 quad_perm:[2,3,0,1] row_mask:0xf bank_mask:0xf bound_ctrl:1
	s_nop 1
	v_add_f32_dpp v37, v37, v37 row_half_mirror row_mask:0xf bank_mask:0xf bound_ctrl:1
	s_nop 1
	v_add_f32_dpp v37, v37, v37 row_mirror row_mask:0xf bank_mask:0xf bound_ctrl:1
	s_nop 0
	v_readlane_b32 s61, v37, 0
	v_readlane_b32 s71, v37, 16
	v_readlane_b32 s70, v37, 32
	v_readlane_b32 s62, v37, 48
	v_cvt_pk_bf16_f32 v37, v57, s0
	ds_write_b16 v108, v37 offset:36864
	v_mul_f32_e32 v37, v42, v42
	s_nop 1
	v_mov_b32_dpp v37, v37 quad_perm:[1,0,3,2] row_mask:0xf bank_mask:0xf bound_ctrl:1
	v_fmac_f32_e32 v37, v42, v42
	s_nop 1
	v_add_f32_dpp v37, v37, v37 quad_perm:[2,3,0,1] row_mask:0xf bank_mask:0xf bound_ctrl:1
	s_nop 1
	v_add_f32_dpp v37, v37, v37 row_half_mirror row_mask:0xf bank_mask:0xf bound_ctrl:1
	s_nop 1
	v_add_f32_dpp v37, v37, v37 row_mirror row_mask:0xf bank_mask:0xf bound_ctrl:1
	s_nop 0
	v_readlane_b32 s39, v37, 0
	v_readlane_b32 s41, v37, 16
	v_readlane_b32 s40, v37, 32
	v_readlane_b32 s60, v37, 48
	v_cvt_pk_bf16_f32 v37, v63, s0
	ds_write_b16 v108, v37 offset:37008
	v_mul_f32_e32 v37, v41, v41
	s_nop 1
	v_mov_b32_dpp v37, v37 quad_perm:[1,0,3,2] row_mask:0xf bank_mask:0xf bound_ctrl:1
	v_fmac_f32_e32 v37, v41, v41
	s_nop 1
	v_add_f32_dpp v37, v37, v37 quad_perm:[2,3,0,1] row_mask:0xf bank_mask:0xf bound_ctrl:1
	s_nop 1
	v_add_f32_dpp v37, v37, v37 row_half_mirror row_mask:0xf bank_mask:0xf bound_ctrl:1
	s_nop 1
	v_add_f32_dpp v37, v37, v37 row_mirror row_mask:0xf bank_mask:0xf bound_ctrl:1
	s_nop 0
	v_readlane_b32 s53, v37, 0
	v_readlane_b32 s55, v37, 16
	v_readlane_b32 s54, v37, 32
	v_readlane_b32 s38, v37, 48
	v_cvt_pk_bf16_f32 v37, v65, s0
	ds_write_b16 v108, v37 offset:37152
	v_mul_f32_e32 v37, v40, v40
	s_nop 1
	v_mov_b32_dpp v37, v37 quad_perm:[1,0,3,2] row_mask:0xf bank_mask:0xf bound_ctrl:1
	v_fmac_f32_e32 v37, v40, v40
	s_nop 1
	v_add_f32_dpp v37, v37, v37 quad_perm:[2,3,0,1] row_mask:0xf bank_mask:0xf bound_ctrl:1
	s_nop 1
	v_add_f32_dpp v37, v37, v37 row_half_mirror row_mask:0xf bank_mask:0xf bound_ctrl:1
	s_nop 1
	v_add_f32_dpp v37, v37, v37 row_mirror row_mask:0xf bank_mask:0xf bound_ctrl:1
	s_nop 0
	v_readlane_b32 s49, v37, 0
	v_readlane_b32 s51, v37, 16
	v_readlane_b32 s50, v37, 32
	v_readlane_b32 s52, v37, 48
	v_cvt_pk_bf16_f32 v37, v67, s0
	ds_write_b16 v108, v37 offset:37296
	v_mul_f32_e32 v37, v38, v38
	s_nop 1
	v_mov_b32_dpp v37, v37 quad_perm:[1,0,3,2] row_mask:0xf bank_mask:0xf bound_ctrl:1
	v_fmac_f32_e32 v37, v38, v38
	s_nop 1
	v_add_f32_dpp v37, v37, v37 quad_perm:[2,3,0,1] row_mask:0xf bank_mask:0xf bound_ctrl:1
	s_nop 1
	v_add_f32_dpp v37, v37, v37 row_half_mirror row_mask:0xf bank_mask:0xf bound_ctrl:1
	s_nop 1
	v_add_f32_dpp v37, v37, v37 row_mirror row_mask:0xf bank_mask:0xf bound_ctrl:1
	s_nop 0
	v_readlane_b32 s45, v37, 0
	v_readlane_b32 s47, v37, 16
	v_readlane_b32 s46, v37, 32
	v_readlane_b32 s48, v37, 48
	v_cvt_pk_bf16_f32 v37, v74, s0
	ds_write_b16 v108, v37 offset:37440
	v_mul_f32_e32 v37, v23, v44
	v_mul_f32_e32 v39, v37, v37
	s_nop 1
	v_mov_b32_dpp v39, v39 quad_perm:[1,0,3,2] row_mask:0xf bank_mask:0xf bound_ctrl:1
	v_fmac_f32_e32 v39, v37, v37
	s_nop 1
	v_add_f32_dpp v39, v39, v39 quad_perm:[2,3,0,1] row_mask:0xf bank_mask:0xf bound_ctrl:1
	s_nop 1
	v_add_f32_dpp v39, v39, v39 row_half_mirror row_mask:0xf bank_mask:0xf bound_ctrl:1
	s_nop 1
	v_add_f32_dpp v39, v39, v39 row_mirror row_mask:0xf bank_mask:0xf bound_ctrl:1
	s_nop 0
	v_readlane_b32 s3, v39, 0
	v_readlane_b32 s37, v39, 16
	v_readlane_b32 s36, v39, 32
; #define LAS __attribute__((address_space(3)))
; __device__ __forceinline__ void rwkvA_phase(const Frame& F, int l) {
;     ...
;                 const float kkr = k * kkc;
;                 const float nrm = sqrtf(wave_sum(kkr * kkr, F.lane));
;                 kk_[e] = kkr * __builtin_amdgcn_rcpf(fmaxf(nrm, 1e-12f));
;                 b_[e] = kk_[e] * a;
;                 kd_[e] = k * (1.0f + (a - 1.0f) * kac);
;                 run += lw_[e]; cl_[e] = run;
;                 *(LAS bf16_t*)(L + O_V + i * CS + F.lane * 2) = f2bf(pv_[e]);
;             }
;             if (task + tstride < tend) RA_LOAD(task + tstride);
	v_readlane_b32 s44, v39, 48
	v_cvt_pk_bf16_f32 v39, v78, s0
	ds_write_b16 v108, v39 offset:37584
	v_mul_f32_e32 v39, v22, v44
	v_mul_f32_e32 v45, v39, v39
	v_mul_f32_e32 v44, v20, v44
	s_nop 0
	v_mov_b32_dpp v45, v45 quad_perm:[1,0,3,2] row_mask:0xf bank_mask:0xf bound_ctrl:1
	v_fmac_f32_e32 v45, v39, v39
	s_nop 1
	v_add_f32_dpp v45, v45, v45 quad_perm:[2,3,0,1] row_mask:0xf bank_mask:0xf bound_ctrl:1
	s_nop 1
	v_add_f32_dpp v45, v45, v45 row_half_mirror row_mask:0xf bank_mask:0xf bound_ctrl:1
	s_nop 1
	v_add_f32_dpp v45, v45, v45 row_mirror row_mask:0xf bank_mask:0xf bound_ctrl:1
	s_nop 0
	v_readlane_b32 s67, v45, 0
	v_readlane_b32 s81, v45, 16
	v_readlane_b32 s80, v45, 32
	v_readlane_b32 s58, v45, 48
	v_cvt_pk_bf16_f32 v45, v91, s0
	ds_write_b16 v108, v45 offset:37728
	v_mul_f32_e32 v45, v44, v44
	s_nop 1
	v_mov_b32_dpp v45, v45 quad_perm:[1,0,3,2] row_mask:0xf bank_mask:0xf bound_ctrl:1
	v_fmac_f32_e32 v45, v44, v44
	s_nop 1
	v_add_f32_dpp v45, v45, v45 quad_perm:[2,3,0,1] row_mask:0xf bank_mask:0xf bound_ctrl:1
	s_nop 1
	v_add_f32_dpp v45, v45, v45 row_half_mirror row_mask:0xf bank_mask:0xf bound_ctrl:1
	s_nop 1
	v_add_f32_dpp v45, v45, v45 row_mirror row_mask:0xf bank_mask:0xf bound_ctrl:1
	s_nop 0
	v_readlane_b32 s63, v45, 0
	v_readlane_b32 s65, v45, 16
	v_readlane_b32 s64, v45, 32
	v_readlane_b32 s66, v45, 48
	v_cvt_pk_bf16_f32 v45, v106, s0
	ds_write_b16 v108, v45 offset:37872
	s_cbranch_vccnz .LBB0_752
	s_mul_hi_i32 s68, s42, 0x3e0f83e1
	s_lshr_b32 s69, s68, 31
	s_ashr_i32 s68, s68, 5
	s_add_i32 s56, s68, s69
	s_mul_i32 s68, s56, 0xffffff7c
	s_add_i32 s68, s68, s42
	s_lshl_b32 s68, s68, 6
	s_bfe_i32 s69, s56, 0x10000
	s_mov_b32 s76, s96
	s_and_b32 s96, s56, 1
	s_add_i32 s68, s68, s83
	s_cmpk_lt_i32 s68, 0x100
	s_movk_i32 s72, 0xff00
	s_mov_b32 s77, s97
	s_cselect_b32 s97, 0x2000, s72
	s_add_i32 s97, s97, s68
	s_sub_i32 s68, 0x20ff, s68
	s_cmp_eq_u32 s96, 0
	s_cselect_b32 vcc_lo, s97, s68
	s_movk_i32 s68, 0xf000
	s_cselect_b32 s68, 0x1000, s68
	s_lshl_b32 s56, s56, 5
	s_ashr_i32 vcc_hi, vcc_lo, 31
	s_andn2_b32 s56, s56, 63
	s_lshl_b64 vcc, vcc, 10
	s_ashr_i32 s97, s56, 31
	s_add_u32 vcc_lo, vcc_lo, s56
	s_addc_u32 vcc_hi, vcc_hi, s97
	v_lshl_add_u64 v[46:47], vcc, 0, v[198:199]
	v_readlane_b32 s72, v255, 8
	v_lshlrev_b64 v[46:47], 2, v[46:47]
	v_readlane_b32 s73, v255, 9
	s_mul_i32 s96, s96, 0x2100000
	v_readlane_b32 s56, v255, 18
	v_lshl_add_u64 v[48:49], s[72:73], 0, v[46:47]
	v_readlane_b32 s72, v255, 10
	s_add_u32 vcc_lo, s56, s96
	v_readlane_b32 s56, v255, 19
	v_readlane_b32 s73, v255, 11
	s_addc_u32 vcc_hi, s56, 0
	v_readlane_b32 s56, v255, 20
	v_lshl_add_u64 v[50:51], s[72:73], 0, v[46:47]
	v_readlane_b32 s72, v255, 6
	v_lshl_add_u64 v[54:55], vcc, 0, v[46:47]
	s_add_u32 vcc_lo, s56, s96
	v_readlane_b32 s56, v255, 21
	v_readlane_b32 s73, v255, 7
	s_addc_u32 vcc_hi, s56, 0
	s_mov_b32 s97, s77
	v_lshl_add_u64 v[52:53], s[72:73], 0, v[46:47]
	v_lshl_add_u64 v[46:47], vcc, 0, v[46:47]
	global_load_dword v138, v[48:49], off
	global_load_dword v57, v[50:51], off
	global_load_dword v137, v[52:53], off
	global_load_dword v136, v[46:47], off
	global_load_dword v127, v[54:55], off
	v_lshl_add_u64 v[48:49], v[48:49], 0, s[68:69]
	v_lshl_add_u64 v[50:51], v[50:51], 0, s[68:69]
	v_lshl_add_u64 v[46:47], v[46:47], 0, s[68:69]
	v_lshl_add_u64 v[54:55], v[54:55], 0, s[68:69]
	global_load_dword v139, v[48:49], off
	global_load_dword v63, v[50:51], off
	global_load_dword v140, v[54:55], off
	global_load_dword v141, v[46:47], off
	v_lshl_add_u64 v[48:49], v[48:49], 0, s[68:69]
	v_lshl_add_u64 v[50:51], v[50:51], 0, s[68:69]
	v_lshl_add_u64 v[46:47], v[46:47], 0, s[68:69]
	v_lshl_add_u64 v[54:55], v[54:55], 0, s[68:69]
	global_load_dword v145, v[48:49], off
	global_load_dword v65, v[50:51], off
	global_load_dword v143, v[54:55], off
	global_load_dword v144, v[46:47], off
	v_lshl_add_u64 v[48:49], v[48:49], 0, s[68:69]
	v_lshl_add_u64 v[50:51], v[50:51], 0, s[68:69]
	v_lshl_add_u64 v[46:47], v[46:47], 0, s[68:69]
	v_lshl_add_u64 v[54:55], v[54:55], 0, s[68:69]
	global_load_dword v150, v[48:49], off
	global_load_dword v67, v[50:51], off
	global_load_dword v147, v[54:55], off
	global_load_dword v148, v[46:47], off
	v_lshl_add_u64 v[48:49], v[48:49], 0, s[68:69]
	v_lshl_add_u64 v[50:51], v[50:51], 0, s[68:69]
	v_lshl_add_u64 v[46:47], v[46:47], 0, s[68:69]
	v_lshl_add_u64 v[54:55], v[54:55], 0, s[68:69]
	global_load_dword v151, v[48:49], off
	global_load_dword v74, v[50:51], off
	global_load_dword v153, v[54:55], off
	global_load_dword v154, v[46:47], off
	v_lshl_add_u64 v[48:49], v[48:49], 0, s[68:69]
	v_lshl_add_u64 v[50:51], v[50:51], 0, s[68:69]
	v_lshl_add_u64 v[46:47], v[46:47], 0, s[68:69]
	v_lshl_add_u64 v[54:55], v[54:55], 0, s[68:69]
	global_load_dword v157, v[48:49], off
	global_load_dword v78, v[50:51], off
	global_load_dword v155, v[54:55], off
	global_load_dword v156, v[46:47], off
	v_lshl_add_u64 v[48:49], v[48:49], 0, s[68:69]
	v_lshl_add_u64 v[50:51], v[50:51], 0, s[68:69]
	v_lshl_add_u64 v[46:47], v[46:47], 0, s[68:69]
	v_lshl_add_u64 v[54:55], v[54:55], 0, s[68:69]
	v_lshl_add_u64 v[52:53], v[52:53], 0, s[68:69]
	global_load_dword v159, v[48:49], off
	global_load_dword v91, v[50:51], off
	global_load_dword v160, v[54:55], off
	global_load_dword v161, v[46:47], off
	v_lshl_add_u64 v[48:49], v[48:49], 0, s[68:69]
	v_lshl_add_u64 v[46:47], v[46:47], 0, s[68:69]
	global_load_dword v142, v[52:53], off
	global_load_dword v164, v[48:49], off
	global_load_dword v163, v[46:47], off
	v_lshl_add_u64 v[52:53], v[52:53], 0, s[68:69]
	v_lshl_add_u64 v[48:49], v[50:51], 0, s[68:69]
	global_load_dword v146, v[52:53], off
	global_load_dword v106, v[48:49], off
	v_lshl_add_u64 v[52:53], v[52:53], 0, s[68:69]
	global_load_dword v149, v[52:53], off
	v_lshl_add_u64 v[52:53], v[52:53], 0, s[68:69]
	global_load_dword v152, v[52:53], off
	v_lshl_add_u64 v[52:53], v[52:53], 0, s[68:69]
	global_load_dword v158, v[52:53], off
	v_lshl_add_u64 v[52:53], v[52:53], 0, s[68:69]
	v_lshl_add_u64 v[46:47], v[54:55], 0, s[68:69]
	global_load_dword v166, v[46:47], off
	v_lshl_add_u64 v[48:49], v[52:53], 0, s[68:69]
	global_load_dword v162, v[52:53], off
	global_load_dword v165, v[48:49], off
	s_mov_b32 s96, s76
	v_readlane_b32 s76, v254, 57
	v_readlane_b32 s77, v254, 58

; __device__ __forceinline__ float sigmoidf_(float x) { return __builtin_amdgcn_rcpf(1.0f + __expf(-x)); }
; __device__ __forceinline__ void rwkvA_phase(const Frame& F, int l) {
;     ...
;             for (int e = 0; e < 8; ++e) {
;                 const int i = F.wave * 8 + e;
;                 const float k = pk_[e], a = sigmoidf_(pza_[e]);
;                 lw_[e] = -0.6065306597126334f * sigmoidf_(pzw_[e]);
;                 r_[e] = pr_[e];
;                 const float kkr = k * kkc;
;                 const float nrm = sqrtf(wave_sum(kkr * kkr, F.lane));
;                 kk_[e] = kkr * __builtin_amdgcn_rcpf(fmaxf(nrm, 1e-12f));
;                 b_[e] = kk_[e] * a;
;                 kd_[e] = k * (1.0f + (a - 1.0f) * kac);
;                 run += lw_[e]; cl_[e] = run;
.LBB0_754:
	v_readlane_b32 s72, v255, 35
	v_readlane_b32 s73, v255, 36
	v_mul_f32_e32 v69, 0xbf1b4598, v54
	v_mul_f32_e32 v54, 0xbf1b4598, v168
	v_cndmask_b32_e64 v168, 0, v172, s[72:73]
	v_readlane_b32 s72, v255, 37
	v_readlane_b32 s73, v255, 38
	s_mov_b32 s56, 0xf800000
	v_mul_f32_e32 v29, 0xbfb8aa3b, v29
	v_cndmask_b32_e64 v11, 0, v11, s[72:73]
	v_readlane_b32 s72, v255, 39
	v_readlane_b32 s73, v255, 40
	v_add_f32_e32 v11, v168, v11
	v_exp_f32_e32 v29, v29
	v_cndmask_b32_e64 v8, 0, v8, s[72:73]
	v_readlane_b32 s72, v255, 41
	v_readlane_b32 s73, v255, 42
	v_add_f32_e32 v8, v11, v8
	v_mov_b32_e32 v11, s60
	v_cndmask_b32_e64 v9, 0, v9, s[72:73]
	v_readlane_b32 s72, v255, 43
	v_readlane_b32 s73, v255, 44
	v_add_f32_e32 v8, v8, v9
	v_add_f32_e32 v11, s40, v11
	v_cndmask_b32_e64 v6, 0, v6, s[72:73]
	v_readlane_b32 s72, v255, 45
	v_readlane_b32 s73, v255, 46
	v_add_f32_e32 v6, v8, v6
	v_add_f32_e32 v29, 1.0, v29
	v_cndmask_b32_e64 v7, 0, v7, s[72:73]
	v_readlane_b32 s72, v255, 47
	v_readlane_b32 s73, v255, 48
	v_add_f32_e32 v6, v6, v7
	v_mov_b32_e32 v7, s62
	v_cndmask_b32_e64 v4, 0, v4, s[72:73]
	v_readlane_b32 s72, v255, 49
	v_readlane_b32 s73, v255, 50
	v_add_f32_e32 v4, v6, v4
	v_add_f32_e32 v7, s70, v7
	v_cndmask_b32_e64 v5, 0, v5, s[72:73]
	v_add_f32_e32 v4, v4, v5
	v_mul_f32_e32 v5, 0xbfb8aa3b, v35
	v_exp_f32_e32 v5, v5
	v_rcp_f32_e32 v29, v29
	v_mul_f32_e32 v28, 0xbfb8aa3b, v28
	v_exp_f32_e32 v28, v28
	v_add_f32_e32 v5, 1.0, v5
	v_rcp_f32_e32 v6, v5
	v_mov_b32_e32 v5, s71
	v_add_f32_e32 v5, s61, v5
	v_add_f32_e32 v5, v5, v7
	v_cmp_gt_f32_e32 vcc, s56, v5
	v_mul_f32_e32 v7, 0x4f800000, v5
	v_add_f32_e32 v28, 1.0, v28
	v_cndmask_b32_e32 v5, v5, v7, vcc
	v_sqrt_f32_e32 v7, v5
	v_rcp_f32_e32 v28, v28
	v_mul_f32_e32 v25, 0xbfb8aa3b, v25
	v_exp_f32_e32 v25, v25
	v_add_u32_e32 v8, -1, v7
	v_fma_f32 v9, -v8, v7, v5
	v_cmp_ge_f32_e64 s[70:71], 0, v9
	v_add_u32_e32 v9, 1, v7
	v_add_f32_e32 v25, 1.0, v25
	v_cndmask_b32_e64 v8, v7, v8, s[70:71]
	v_fma_f32 v7, -v9, v7, v5
	v_cmp_lt_f32_e64 s[70:71], 0, v7
	v_rcp_f32_e32 v25, v25
	v_mul_f32_e32 v24, 0xbfb8aa3b, v24
	v_cndmask_b32_e64 v7, v8, v9, s[70:71]
	v_mul_f32_e32 v8, 0x37800000, v7
	v_cndmask_b32_e32 v7, v7, v8, vcc
	v_mul_f32_e32 v8, 0xbfb8aa3b, v34
	v_exp_f32_e32 v8, v8
	v_cmp_class_f32_e32 vcc, v5, v219
	v_exp_f32_e32 v24, v24
	v_mul_f32_e32 v21, 0xbfb8aa3b, v21
	v_add_f32_e32 v8, 1.0, v8
	v_cndmask_b32_e32 v5, v7, v5, vcc
	v_rcp_f32_e32 v9, v8
	v_mov_b32_e32 v8, s41
	v_max_f32_e32 v5, 0x2b8cbccc, v5
	v_add_f32_e32 v8, s39, v8
	v_rcp_f32_e32 v5, v5
	v_add_f32_e32 v8, v8, v11
	v_cmp_gt_f32_e32 vcc, s56, v8
	v_mul_f32_e32 v11, 0x4f800000, v8
	v_mul_f32_e32 v7, v43, v5
	v_cndmask_b32_e32 v8, v8, v11, vcc
	v_sqrt_f32_e32 v11, v8
	v_mul_f32_e32 v5, v6, v7
	v_add_f32_e32 v6, -1.0, v6
	s_waitcnt vmcnt(40)
	v_fma_f32 v6, v6, v36, 1.0
	v_mul_f32_e32 v6, v33, v6
	v_add_u32_e32 v33, -1, v11
	v_fma_f32 v34, -v33, v11, v8
	v_cmp_ge_f32_e64 s[70:71], 0, v34
	v_add_u32_e32 v34, 1, v11
	v_add_f32_e32 v24, 1.0, v24
	v_cndmask_b32_e64 v33, v11, v33, s[70:71]
	v_fma_f32 v11, -v34, v11, v8
	v_cmp_lt_f32_e64 s[70:71], 0, v11
	v_rcp_f32_e32 v24, v24
	v_exp_f32_e32 v21, v21
	v_cndmask_b32_e64 v11, v33, v34, s[70:71]
	v_mul_f32_e32 v33, 0x37800000, v11
	v_cndmask_b32_e32 v11, v11, v33, vcc
	v_cmp_class_f32_e32 vcc, v8, v219
	v_mov_b32_e32 v33, s38
	v_add_f32_e32 v33, s54, v33
	v_cndmask_b32_e32 v8, v11, v8, vcc
	v_max_f32_e32 v8, 0x2b8cbccc, v8
	v_rcp_f32_e32 v8, v8
	v_add_f32_e32 v21, 1.0, v21
	v_rcp_f32_e32 v21, v21
	v_mul_f32_e32 v167, 0xbf1b4598, v47
	v_mul_f32_e32 v11, v42, v8
	v_mul_f32_e32 v8, v9, v11
	v_add_f32_e32 v9, -1.0, v9
	v_fma_f32 v9, v9, v36, 1.0
	v_mul_f32_e32 v9, v31, v9
	v_mul_f32_e32 v31, 0xbfb8aa3b, v32
	v_exp_f32_e32 v31, v31
	v_mul_f32_e32 v131, 0xbf1b4598, v49
	v_mul_f32_e32 v130, 0xbf1b4598, v52
	v_mul_f32_e32 v52, 0xbf1b4598, v169
	v_add_f32_e32 v31, 1.0, v31
	v_rcp_f32_e32 v32, v31
	v_mov_b32_e32 v31, s55
	v_add_f32_e32 v31, s53, v31
	v_add_f32_e32 v31, v31, v33
	v_cmp_gt_f32_e32 vcc, s56, v31
	v_mul_f32_e32 v33, 0x4f800000, v31
	v_mul_f32_e32 v49, 0xbf1b4598, v170
	v_cndmask_b32_e32 v31, v31, v33, vcc
	v_sqrt_f32_e32 v33, v31
	v_mul_f32_e32 v47, 0xbf1b4598, v171
	s_mov_b64 s[72:73], s[8:9]
	s_mov_b64 s[74:75], s[94:95]
	v_add_u32_e32 v34, -1, v33
	v_fma_f32 v35, -v34, v33, v31
	v_cmp_ge_f32_e64 s[70:71], 0, v35
	v_add_u32_e32 v35, 1, v33
	s_nop 0
	v_cndmask_b32_e64 v34, v33, v34, s[70:71]
	v_fma_f32 v33, -v35, v33, v31
	v_cmp_lt_f32_e64 s[70:71], 0, v33
	s_nop 1
	v_cndmask_b32_e64 v33, v34, v35, s[70:71]
	v_mul_f32_e32 v34, 0x37800000, v33
	v_cndmask_b32_e32 v33, v33, v34, vcc
	v_cmp_class_f32_e32 vcc, v31, v219
	v_mov_b32_e32 v34, s52
	v_add_f32_e32 v34, s50, v34
	v_cndmask_b32_e32 v31, v33, v31, vcc
	v_max_f32_e32 v31, 0x2b8cbccc, v31
	v_rcp_f32_e32 v31, v31
	s_nop 0
	v_mul_f32_e32 v33, v41, v31
	v_mul_f32_e32 v31, v32, v33
	v_add_f32_e32 v32, -1.0, v32
	v_fma_f32 v32, v32, v36, 1.0
	v_mul_f32_e32 v30, v30, v32
	v_mov_b32_e32 v32, s51
	v_add_f32_e32 v32, s49, v32
	v_add_f32_e32 v32, v32, v34
	v_cmp_gt_f32_e32 vcc, s56, v32
	v_mul_f32_e32 v34, 0x4f800000, v32
	s_nop 0
	v_cndmask_b32_e32 v32, v32, v34, vcc
	v_sqrt_f32_e32 v34, v32
	s_nop 0
	v_add_u32_e32 v35, -1, v34
	v_fma_f32 v41, -v35, v34, v32
	v_cmp_ge_f32_e64 s[70:71], 0, v41
	v_add_u32_e32 v41, 1, v34
	s_nop 0
	v_cndmask_b32_e64 v35, v34, v35, s[70:71]
	v_fma_f32 v34, -v41, v34, v32
	v_cmp_lt_f32_e64 s[70:71], 0, v34
	s_nop 1
	v_cndmask_b32_e64 v34, v35, v41, s[70:71]
	v_mul_f32_e32 v35, 0x37800000, v34
	v_cndmask_b32_e32 v34, v34, v35, vcc
	v_cmp_class_f32_e32 vcc, v32, v219
	v_mov_b32_e32 v35, s48
	v_add_f32_e32 v35, s46, v35
; #define LAS __attribute__((address_space(3)))
; __device__ __forceinline__ void lds_barrier() { asm volatile("s_waitcnt lgkmcnt(0)\n\ts_barrier" ::: "memory"); }
; __device__ __forceinline__ void rwkvA_phase(const Frame& F, int l) {
;     ...
;                 const float nrm = sqrtf(wave_sum(kkr * kkr, F.lane));
;                 kk_[e] = kkr * __builtin_amdgcn_rcpf(fmaxf(nrm, 1e-12f));
;                 b_[e] = kk_[e] * a;
;                 kd_[e] = k * (1.0f + (a - 1.0f) * kac);
;                 run += lw_[e]; cl_[e] = run;
;                 *(LAS bf16_t*)(L + O_V + i * CS + F.lane * 2) = f2bf(pv_[e]);
;             }
;             if (task + tstride < tend) RA_LOAD(task + tstride);
;             tot[F.wave * 64 + F.lane] = run;
;             lds_barrier();
;             float off = 0.f, all = 0.f;
; #pragma unroll
;             for (int w = 0; w < 8; ++w) { const float t = tot[w * 64 + F.lane]; all += t; off += (w < F.wave) ? t : 0.f; }
;             if (F.wave == 0) gL[F.lane] = __expf(all);
; #pragma unroll
;             for (int e = 0; e < 8; ++e) {
;                 const int i = F.wave * 8 + e;
;                 const float cum = off + cl_[e], cumm = cum - lw_[e];
;                 const float ec = __expf(cum), em = __expf(cumm), ei = __expf(-cum), eh = __expf(all - cum);
;                 const int o = i * CS + F.lane * 2;
;                 *(LAS bf16_t*)(L + O_KT + o) = f2bf(kk_[e] * em);
;                 *(LAS bf16_t*)(L + O_RT + o) = f2bf(r_[e] * ec);
;                 *(LAS bf16_t*)(L + O_BB + o) = f2bf(b_[e] * ei);
;                 *(LAS bf16_t*)(L + O_KB + o) = f2bf(kd_[e] * ei);
;                 *(LAS bf16_t*)(L + O_BH + o) = f2bf(b_[e] * eh);
;                 *(LAS bf16_t*)(L + O_KH + o) = f2bf(kd_[e] * eh);
;             }
	v_cndmask_b32_e32 v32, v34, v32, vcc
	v_max_f32_e32 v32, 0x2b8cbccc, v32
	v_rcp_f32_e32 v32, v32
	s_nop 0
	v_mul_f32_e32 v32, v40, v32
	v_mul_f32_e32 v34, v29, v32
	v_add_f32_e32 v29, -1.0, v29
	v_fma_f32 v29, v29, v36, 1.0
	v_mul_f32_e32 v27, v27, v29
	v_mov_b32_e32 v29, s47
	v_add_f32_e32 v29, s45, v29
	v_add_f32_e32 v29, v29, v35
	v_cmp_gt_f32_e32 vcc, s56, v29
	v_mul_f32_e32 v35, 0x4f800000, v29
	s_nop 0
	v_cndmask_b32_e32 v29, v29, v35, vcc
	v_sqrt_f32_e32 v35, v29
	s_nop 0
	v_add_u32_e32 v40, -1, v35
	v_fma_f32 v41, -v40, v35, v29
	v_cmp_ge_f32_e64 s[70:71], 0, v41
	v_add_u32_e32 v41, 1, v35
	s_nop 0
	v_cndmask_b32_e64 v40, v35, v40, s[70:71]
	v_fma_f32 v35, -v41, v35, v29
	v_cmp_lt_f32_e64 s[70:71], 0, v35
	s_nop 1
	v_cndmask_b32_e64 v35, v40, v41, s[70:71]
	v_mul_f32_e32 v40, 0x37800000, v35
	v_cndmask_b32_e32 v35, v35, v40, vcc
	v_cmp_class_f32_e32 vcc, v29, v219
	s_nop 1
	v_cndmask_b32_e32 v29, v35, v29, vcc
	v_max_f32_e32 v29, 0x2b8cbccc, v29
	v_rcp_f32_e32 v29, v29
	s_nop 0
	v_mul_f32_e32 v29, v38, v29
	v_mul_f32_e32 v35, v28, v29
	v_add_f32_e32 v28, -1.0, v28
	v_fma_f32 v28, v28, v36, 1.0
	v_mul_f32_e32 v26, v26, v28
	v_mov_b32_e32 v28, s37
	v_mov_b32_e32 v38, s44
	v_add_f32_e32 v28, s3, v28
	v_add_f32_e32 v38, s36, v38
	v_add_f32_e32 v28, v28, v38
	v_cmp_gt_f32_e32 vcc, s56, v28
	v_mul_f32_e32 v38, 0x4f800000, v28
	s_nop 0
	v_cndmask_b32_e32 v28, v28, v38, vcc
	v_sqrt_f32_e32 v38, v28
	s_nop 0
	v_add_u32_e32 v40, -1, v38
	v_fma_f32 v41, -v40, v38, v28
	v_cmp_ge_f32_e64 s[70:71], 0, v41
	v_add_u32_e32 v41, 1, v38
	s_nop 0
	v_cndmask_b32_e64 v40, v38, v40, s[70:71]
	v_fma_f32 v38, -v41, v38, v28
	v_cmp_lt_f32_e64 s[70:71], 0, v38
	s_nop 1
	v_cndmask_b32_e64 v38, v40, v41, s[70:71]
	v_mul_f32_e32 v40, 0x37800000, v38
	v_cndmask_b32_e32 v38, v38, v40, vcc
	v_cmp_class_f32_e32 vcc, v28, v219
	s_nop 1
	v_cndmask_b32_e32 v28, v38, v28, vcc
	v_max_f32_e32 v28, 0x2b8cbccc, v28
	v_rcp_f32_e32 v28, v28
	v_mov_b32_e32 v38, s58
	v_add_f32_e32 v38, s80, v38
	v_mul_f32_e32 v28, v37, v28
	v_mul_f32_e32 v37, v25, v28
	v_add_f32_e32 v25, -1.0, v25
	v_fma_f32 v25, v25, v36, 1.0
	v_mul_f32_e32 v23, v23, v25
	v_mov_b32_e32 v25, s81
	v_add_f32_e32 v25, s67, v25
	v_add_f32_e32 v25, v25, v38
	v_cmp_gt_f32_e32 vcc, s56, v25
	v_mul_f32_e32 v38, 0x4f800000, v25
	s_nop 0
	v_cndmask_b32_e32 v25, v25, v38, vcc
	v_sqrt_f32_e32 v38, v25
	s_nop 0
	v_add_u32_e32 v40, -1, v38
	v_fma_f32 v41, -v40, v38, v25
	v_cmp_ge_f32_e64 s[70:71], 0, v41
	v_add_u32_e32 v41, 1, v38
	s_nop 0
	v_cndmask_b32_e64 v40, v38, v40, s[70:71]
	v_fma_f32 v38, -v41, v38, v25
	v_cmp_lt_f32_e64 s[70:71], 0, v38
	s_nop 1
	v_cndmask_b32_e64 v38, v40, v41, s[70:71]
	v_mul_f32_e32 v40, 0x37800000, v38
	v_cndmask_b32_e32 v38, v38, v40, vcc
	v_cmp_class_f32_e32 vcc, v25, v219
	s_nop 1
	v_cndmask_b32_e32 v25, v38, v25, vcc
	v_max_f32_e32 v25, 0x2b8cbccc, v25
	v_rcp_f32_e32 v25, v25
	s_nop 0
	v_mul_f32_e32 v25, v39, v25
	v_mul_f32_e32 v38, v24, v25
	v_add_f32_e32 v24, -1.0, v24
	v_fma_f32 v24, v24, v36, 1.0
	v_mul_f32_e32 v22, v22, v24
	v_mov_b32_e32 v24, s65
	v_mov_b32_e32 v39, s66
	v_add_f32_e32 v24, s63, v24
	v_add_f32_e32 v39, s64, v39
	v_add_f32_e32 v24, v24, v39
	v_cmp_gt_f32_e32 vcc, s56, v24
	v_mul_f32_e32 v39, 0x4f800000, v24
	s_nop 0
	v_cndmask_b32_e32 v24, v24, v39, vcc
	v_sqrt_f32_e32 v39, v24
	s_nop 0
	v_add_u32_e32 v40, -1, v39
	v_fma_f32 v41, -v40, v39, v24
	v_cmp_ge_f32_e64 s[70:71], 0, v41
	v_add_u32_e32 v41, 1, v39
	s_nop 0
	v_cndmask_b32_e64 v40, v39, v40, s[70:71]
	v_fma_f32 v39, -v41, v39, v24
	v_cmp_lt_f32_e64 s[70:71], 0, v39
	s_nop 1
	v_cndmask_b32_e64 v39, v40, v41, s[70:71]
	v_mul_f32_e32 v40, 0x37800000, v39
	v_cndmask_b32_e32 v39, v39, v40, vcc
	v_cmp_class_f32_e32 vcc, v24, v219
	s_nop 1
	v_cndmask_b32_e32 v24, v39, v24, vcc
	v_max_f32_e32 v24, 0x2b8cbccc, v24
	v_rcp_f32_e32 v24, v24
	s_and_b64 vcc, exec, s[68:69]
	v_mul_f32_e32 v24, v44, v24
	v_mul_f32_e32 v39, v21, v24
	v_add_f32_e32 v21, -1.0, v21
	v_fma_f32 v21, v21, v36, 1.0
	v_mul_f32_e32 v20, v20, v21
	v_add_f32_e32 v21, v129, v4
	v_sub_f32_e32 v36, v21, v167
	v_mul_f32_e32 v36, 0x3fb8aa3b, v36
	v_exp_f32_e32 v36, v36
	v_mul_f32_e32 v40, 0x3fb8aa3b, v21
	v_exp_f32_e32 v40, v40
	v_mul_f32_e32 v41, 0xbfb8aa3b, v21
	v_sub_f32_e32 v21, v10, v21
	v_mul_f32_e32 v21, 0x3fb8aa3b, v21
	v_exp_f32_e32 v41, v41
	v_exp_f32_e32 v21, v21
	v_mul_f32_e32 v7, v7, v36
	v_cvt_pk_bf16_f32 v7, v7, s0
	ds_write_b16 v108, v7
	v_mul_f32_e32 v7, v12, v40
	v_cvt_pk_bf16_f32 v7, v7, s0
	ds_write_b16 v108, v7 offset:9216
	v_mul_f32_e32 v7, v5, v41
	v_mul_f32_e32 v5, v5, v21
	v_cvt_pk_bf16_f32 v5, v5, s0
	ds_write_b16 v108, v5 offset:18432
	v_mul_f32_e32 v5, v6, v21
	v_cvt_pk_bf16_f32 v5, v5, s0
	v_cvt_pk_bf16_f32 v7, v7, s0
	ds_write_b16 v108, v5 offset:27648
	v_add_f32_e32 v5, v55, v4
	ds_write_b16 v108, v7 offset:46080
	v_mul_f32_e32 v7, v6, v41
	v_sub_f32_e32 v6, v5, v131
	v_mul_f32_e32 v6, 0x3fb8aa3b, v6
	v_cvt_pk_bf16_f32 v7, v7, s0
	v_exp_f32_e32 v6, v6
	ds_write_b16 v108, v7 offset:55296
	v_mul_f32_e32 v7, 0x3fb8aa3b, v5
	v_exp_f32_e32 v7, v7
	v_mul_f32_e32 v12, 0xbfb8aa3b, v5
	v_exp_f32_e32 v12, v12
	v_mul_f32_e32 v6, v11, v6
	v_cvt_pk_bf16_f32 v6, v6, s0
	v_sub_f32_e32 v5, v10, v5
	ds_write_b16 v108, v6 offset:144
	v_mul_f32_e32 v6, v14, v7
	v_mul_f32_e32 v5, 0x3fb8aa3b, v5
	v_cvt_pk_bf16_f32 v6, v6, s0
	v_exp_f32_e32 v5, v5
	ds_write_b16 v108, v6 offset:9360
	v_mul_f32_e32 v6, v8, v12
	v_cvt_pk_bf16_f32 v6, v6, s0
	ds_write_b16 v108, v6 offset:46224
	v_mul_f32_e32 v6, v9, v12
	v_cvt_pk_bf16_f32 v6, v6, s0
	ds_write_b16 v108, v6 offset:55440
	v_mul_f32_e32 v6, v8, v5
	v_mul_f32_e32 v5, v9, v5
	v_cvt_pk_bf16_f32 v5, v5, s0
; #define LAS __attribute__((address_space(3)))
; __device__ __forceinline__ void lds_barrier() { asm volatile("s_waitcnt lgkmcnt(0)\n\ts_barrier" ::: "memory"); }
; __device__ __forceinline__ void rwkvA_phase(const Frame& F, int l) {
;     ...
; #pragma unroll
;             for (int e = 0; e < 8; ++e) {
;                 const int i = F.wave * 8 + e;
;                 const float cum = off + cl_[e], cumm = cum - lw_[e];
;                 const float ec = __expf(cum), em = __expf(cumm), ei = __expf(-cum), eh = __expf(all - cum);
;                 const int o = i * CS + F.lane * 2;
;                 *(LAS bf16_t*)(L + O_KT + o) = f2bf(kk_[e] * em);
;                 *(LAS bf16_t*)(L + O_RT + o) = f2bf(r_[e] * ec);
;                 *(LAS bf16_t*)(L + O_BB + o) = f2bf(b_[e] * ei);
;                 *(LAS bf16_t*)(L + O_KB + o) = f2bf(kd_[e] * ei);
;                 *(LAS bf16_t*)(L + O_BH + o) = f2bf(b_[e] * eh);
;                 *(LAS bf16_t*)(L + O_KH + o) = f2bf(kd_[e] * eh);
;             }
;         }
;         lds_barrier();
	v_cvt_pk_bf16_f32 v6, v6, s0
	ds_write_b16 v108, v5 offset:27792
	v_add_f32_e32 v5, v53, v4
	ds_write_b16 v108, v6 offset:18576
	v_sub_f32_e32 v6, v5, v130
	v_mul_f32_e32 v6, 0x3fb8aa3b, v6
	v_exp_f32_e32 v6, v6
	v_mul_f32_e32 v7, 0x3fb8aa3b, v5
	v_exp_f32_e32 v7, v7
	v_mul_f32_e32 v8, 0xbfb8aa3b, v5
	v_exp_f32_e32 v8, v8
	v_mul_f32_e32 v6, v33, v6
	v_cvt_pk_bf16_f32 v6, v6, s0
	v_sub_f32_e32 v5, v10, v5
	ds_write_b16 v108, v6 offset:288
	v_mul_f32_e32 v6, v13, v7
	v_mul_f32_e32 v5, 0x3fb8aa3b, v5
	v_cvt_pk_bf16_f32 v6, v6, s0
	v_exp_f32_e32 v5, v5
	ds_write_b16 v108, v6 offset:9504
	v_mul_f32_e32 v6, v31, v8
	v_cvt_pk_bf16_f32 v6, v6, s0
	ds_write_b16 v108, v6 offset:46368
	v_mul_f32_e32 v6, v30, v8
	v_cvt_pk_bf16_f32 v6, v6, s0
	ds_write_b16 v108, v6 offset:55584
	v_mul_f32_e32 v6, v31, v5
	v_mul_f32_e32 v5, v30, v5
	v_cvt_pk_bf16_f32 v5, v5, s0
	v_cvt_pk_bf16_f32 v6, v6, s0
	ds_write_b16 v108, v5 offset:27936
	v_add_f32_e32 v5, v51, v4
	ds_write_b16 v108, v6 offset:18720
	v_sub_f32_e32 v6, v5, v69
	v_mul_f32_e32 v6, 0x3fb8aa3b, v6
	v_exp_f32_e32 v6, v6
	v_mul_f32_e32 v7, 0x3fb8aa3b, v5
	v_exp_f32_e32 v7, v7
	v_mul_f32_e32 v8, 0xbfb8aa3b, v5
	v_exp_f32_e32 v8, v8
	v_mul_f32_e32 v6, v32, v6
	v_cvt_pk_bf16_f32 v6, v6, s0
	v_sub_f32_e32 v5, v10, v5
	ds_write_b16 v108, v6 offset:432
	v_mul_f32_e32 v6, v16, v7
	v_mul_f32_e32 v5, 0x3fb8aa3b, v5
	v_cvt_pk_bf16_f32 v6, v6, s0
	v_exp_f32_e32 v5, v5
	ds_write_b16 v108, v6 offset:9648
	v_mul_f32_e32 v6, v34, v8
	v_cvt_pk_bf16_f32 v6, v6, s0
	ds_write_b16 v108, v6 offset:46512
	v_mul_f32_e32 v6, v27, v8
	v_cvt_pk_bf16_f32 v6, v6, s0
	ds_write_b16 v108, v6 offset:55728
	v_mul_f32_e32 v6, v34, v5
	v_mul_f32_e32 v5, v27, v5
	v_cvt_pk_bf16_f32 v5, v5, s0
	v_cvt_pk_bf16_f32 v6, v6, s0
	ds_write_b16 v108, v5 offset:28080
	v_add_f32_e32 v5, v50, v4
	ds_write_b16 v108, v6 offset:18864
	v_sub_f32_e32 v6, v5, v54
	v_mul_f32_e32 v6, 0x3fb8aa3b, v6
	v_exp_f32_e32 v6, v6
	v_mul_f32_e32 v7, 0x3fb8aa3b, v5
	v_exp_f32_e32 v7, v7
	v_mul_f32_e32 v8, 0xbfb8aa3b, v5
	v_exp_f32_e32 v8, v8
	v_mul_f32_e32 v6, v29, v6
	v_cvt_pk_bf16_f32 v6, v6, s0
	v_sub_f32_e32 v5, v10, v5
	ds_write_b16 v108, v6 offset:576
	v_mul_f32_e32 v6, v15, v7
	v_mul_f32_e32 v5, 0x3fb8aa3b, v5
	v_cvt_pk_bf16_f32 v6, v6, s0
	v_exp_f32_e32 v5, v5
	ds_write_b16 v108, v6 offset:9792
	v_mul_f32_e32 v6, v35, v8
	v_cvt_pk_bf16_f32 v6, v6, s0
	ds_write_b16 v108, v6 offset:46656
	v_mul_f32_e32 v6, v26, v8
	v_cvt_pk_bf16_f32 v6, v6, s0
	ds_write_b16 v108, v6 offset:55872
	v_mul_f32_e32 v6, v35, v5
	v_mul_f32_e32 v5, v26, v5
	v_cvt_pk_bf16_f32 v5, v5, s0
	v_cvt_pk_bf16_f32 v6, v6, s0
	ds_write_b16 v108, v5 offset:28224
	v_add_f32_e32 v5, v48, v4
	ds_write_b16 v108, v6 offset:19008
	v_sub_f32_e32 v6, v5, v52
	v_mul_f32_e32 v6, 0x3fb8aa3b, v6
	v_exp_f32_e32 v6, v6
	v_mul_f32_e32 v7, 0x3fb8aa3b, v5
	v_exp_f32_e32 v7, v7
	v_mul_f32_e32 v8, 0xbfb8aa3b, v5
	v_exp_f32_e32 v8, v8
	v_mul_f32_e32 v6, v28, v6
	v_cvt_pk_bf16_f32 v6, v6, s0
	v_sub_f32_e32 v5, v10, v5
	ds_write_b16 v108, v6 offset:720
	v_mul_f32_e32 v6, v17, v7
	v_mul_f32_e32 v5, 0x3fb8aa3b, v5
	v_cvt_pk_bf16_f32 v6, v6, s0
	v_exp_f32_e32 v5, v5
	ds_write_b16 v108, v6 offset:9936
	v_mul_f32_e32 v6, v37, v8
	v_cvt_pk_bf16_f32 v6, v6, s0
	ds_write_b16 v108, v6 offset:46800
	v_mul_f32_e32 v6, v23, v8
	v_cvt_pk_bf16_f32 v6, v6, s0
	ds_write_b16 v108, v6 offset:56016
	v_mul_f32_e32 v6, v37, v5
	v_mul_f32_e32 v5, v23, v5
	v_cvt_pk_bf16_f32 v5, v5, s0
	v_cvt_pk_bf16_f32 v6, v6, s0
	ds_write_b16 v108, v5 offset:28368
	v_add_f32_e32 v5, v46, v4
	ds_write_b16 v108, v6 offset:19152
	v_sub_f32_e32 v6, v5, v49
	v_mul_f32_e32 v6, 0x3fb8aa3b, v6
	v_exp_f32_e32 v6, v6
	v_mul_f32_e32 v7, 0x3fb8aa3b, v5
	v_exp_f32_e32 v7, v7
	v_mul_f32_e32 v8, 0xbfb8aa3b, v5
	v_exp_f32_e32 v8, v8
	v_mul_f32_e32 v6, v25, v6
	v_cvt_pk_bf16_f32 v6, v6, s0
	v_sub_f32_e32 v5, v10, v5
	ds_write_b16 v108, v6 offset:864
	v_mul_f32_e32 v6, v19, v7
	v_mul_f32_e32 v5, 0x3fb8aa3b, v5
	v_cvt_pk_bf16_f32 v6, v6, s0
	v_exp_f32_e32 v5, v5
	ds_write_b16 v108, v6 offset:10080
	v_mul_f32_e32 v6, v38, v8
	v_cvt_pk_bf16_f32 v6, v6, s0
	ds_write_b16 v108, v6 offset:46944
	v_mul_f32_e32 v6, v22, v8
	v_cvt_pk_bf16_f32 v6, v6, s0
	ds_write_b16 v108, v6 offset:56160
	v_mul_f32_e32 v6, v38, v5
	v_mul_f32_e32 v5, v22, v5
	v_cvt_pk_bf16_f32 v5, v5, s0
	v_add_f32_e32 v4, v45, v4
	ds_write_b16 v108, v5 offset:28512
	v_sub_f32_e32 v5, v4, v47
	v_mul_f32_e32 v5, 0x3fb8aa3b, v5
	v_cvt_pk_bf16_f32 v6, v6, s0
	v_exp_f32_e32 v5, v5
	ds_write_b16 v108, v6 offset:19296
	v_mul_f32_e32 v6, 0x3fb8aa3b, v4
	v_exp_f32_e32 v6, v6
	v_mul_f32_e32 v7, 0xbfb8aa3b, v4
	v_exp_f32_e32 v7, v7
	v_mul_f32_e32 v5, v24, v5
	v_cvt_pk_bf16_f32 v5, v5, s0
	v_sub_f32_e32 v4, v10, v4
	ds_write_b16 v108, v5 offset:1008
	v_mul_f32_e32 v5, v18, v6
	v_mul_f32_e32 v4, 0x3fb8aa3b, v4
	v_cvt_pk_bf16_f32 v5, v5, s0
	v_exp_f32_e32 v4, v4
	ds_write_b16 v108, v5 offset:10224
	v_mul_f32_e32 v5, v39, v7
	v_cvt_pk_bf16_f32 v5, v5, s0
	ds_write_b16 v108, v5 offset:47088
	v_mul_f32_e32 v5, v20, v7
	v_cvt_pk_bf16_f32 v5, v5, s0
	ds_write_b16 v108, v5 offset:56304
	v_mul_f32_e32 v5, v39, v4
	v_mul_f32_e32 v4, v20, v4
	v_cvt_pk_bf16_f32 v5, v5, s0
	v_cvt_pk_bf16_f32 v4, v4, s0
	ds_write_b16 v108, v5 offset:19440
	ds_write_b16 v108, v4 offset:28656
	s_waitcnt lgkmcnt(0)
	s_barrier
; #define MFMA_BF(a, b, c) __builtin_amdgcn_mfma_f32_16x16x32_bf16(a, b, c, 0, 0, 0)
; __device__ __forceinline__ void rwkvA_phase(const Frame& F, int l) {
;     ...
;         {
;             f32x4 ab[2] = {z4, z4}, ak[2] = {z4, z4}, rb[2] = {z4, z4}, rk[2] = {z4, z4};
; #pragma unroll
;             for (int ks = 0; ks < 2; ++ks) {
;                 const bf16x8 aK = ch_rowread(L + O_KT, tr, ks, qi, g), aR = ch_rowread(L + O_RT, tr, ks, qi, g);
; #pragma unroll
;                 for (int t = 0; t < 2; ++t) {
;                     const bf16x8 bB = ch_rowread(L + O_BB, tcb + t, ks, qi, g), bK = ch_rowread(L + O_KB, tcb + t, ks, qi, g);
;                     ab[t] = MFMA_BF(aK, bB, ab[t]); ak[t] = MFMA_BF(aK, bK, ak[t]); rb[t] = MFMA_BF(aR, bB, rb[t]); rk[t] = MFMA_BF(aR, bK, rk[t]);
;                 }
;             }
; #pragma unroll
;             for (int t = 0; t < 2; ++t) {
;                 const int col = 16 * (tcb + t) + qi;
; #pragma unroll
;                 for (int jj = 0; jj < 4; ++jj) {
;                     const int row = 16 * tr + 4 * g + jj;
;                     const bool lo = col < row, le = col <= row;
;                     Af[row * CF + col] = lo ? ab[t][jj] : 0.f;
;                     ak[t][jj] = lo ? ak[t][jj] : 0.f; rb[t][jj] = le ? rb[t][jj] : 0.f; rk[t][jj] = le ? rk[t][jj] : 0.f;
;                 }
;                 ch_store_bf16(L + O_AAK, tr, tcb + t, qi, g, ak[t]); ch_store_bf16(L + O_ARB, tr, tcb + t, qi, g, rb[t]); ch_store_bf16(L + O_ARK, tr, tcb + t, qi, g, rk[t]);
;             }
;         }
	ds_read_b128 v[4:7], v125
	ds_read_b128 v[8:11], v125 offset:9216
	ds_read_b128 v[12:15], v114 offset:46080
	ds_read_b128 v[16:19], v114 offset:55296
	ds_read_b128 v[28:31], v115 offset:46080
	ds_read_b128 v[32:35], v115 offset:55296
	s_waitcnt lgkmcnt(3)
	v_mfma_f32_16x16x32_bf16 v[20:23], v[4:7], v[12:15], v[0:3]
	s_waitcnt lgkmcnt(2)
	v_mfma_f32_16x16x32_bf16 v[24:27], v[4:7], v[16:19], v[0:3]
	v_mfma_f32_16x16x32_bf16 v[12:15], v[8:11], v[12:15], v[0:3]
	v_mfma_f32_16x16x32_bf16 v[16:19], v[8:11], v[16:19], v[0:3]
	s_waitcnt lgkmcnt(1)
	v_mfma_f32_16x16x32_bf16 v[36:39], v[4:7], v[28:31], v[0:3]
	s_waitcnt lgkmcnt(0)
	v_mfma_f32_16x16x32_bf16 v[4:7], v[4:7], v[32:35], v[0:3]
	v_mfma_f32_16x16x32_bf16 v[28:31], v[8:11], v[28:31], v[0:3]
	v_mfma_f32_16x16x32_bf16 v[8:11], v[8:11], v[32:35], v[0:3]
	ds_read_b128 v[32:35], v125 offset:64
	ds_read_b128 v[40:43], v125 offset:9280
	ds_read_b128 v[44:47], v114 offset:46144
	ds_read_b128 v[48:51], v114 offset:55360
	s_waitcnt lgkmcnt(1)
	v_mfma_f32_16x16x32_bf16 v[20:23], v[32:35], v[44:47], v[20:23]
	s_waitcnt lgkmcnt(0)
	v_mfma_f32_16x16x32_bf16 v[24:27], v[32:35], v[48:51], v[24:27]
	v_mfma_f32_16x16x32_bf16 v[12:15], v[40:43], v[44:47], v[12:15]
	v_mfma_f32_16x16x32_bf16 v[16:19], v[40:43], v[48:51], v[16:19]
	ds_read_b128 v[44:47], v115 offset:46144
	ds_read_b128 v[48:51], v115 offset:55360
	s_nop 4
	v_cndmask_b32_e64 v14, v14, 0, s[12:13]
	v_cndmask_b32_e64 v15, v15, 0, s[16:17]
	s_waitcnt lgkmcnt(1)
	v_mfma_f32_16x16x32_bf16 v[36:39], v[32:35], v[44:47], v[36:39]
	s_waitcnt lgkmcnt(0)
	v_mfma_f32_16x16x32_bf16 v[4:7], v[32:35], v[48:51], v[4:7]
	v_mfma_f32_16x16x32_bf16 v[32:35], v[40:43], v[48:51], v[8:11]
	s_nop 2
	v_cvt_pk_bf16_f32 v8, v24, s0
	v_cndmask_b32_e64 v10, 0, v8, s[4:5]
	v_cvt_pk_bf16_f32 v8, v16, s0
	v_cndmask_b32_e64 v11, v12, 0, s[6:7]
	v_cndmask_b32_e64 v12, v8, 0, s[6:7]
	v_cvt_pk_bf16_f32 v8, v25, s0
	v_cndmask_b32_e64 v9, 0, v20, s[4:5]
	v_cndmask_b32_e64 v16, v21, 0, s[6:7]
	v_cndmask_b32_e64 v20, v8, 0, s[6:7]
	v_cvt_pk_bf16_f32 v8, v17, s0
	ds_write2_b32 v116, v9, v16 offset1:68
	v_cndmask_b32_e64 v9, v13, 0, s[10:11]
	v_cndmask_b32_e64 v13, v8, 0, s[10:11]
	v_cvt_pk_bf16_f32 v8, v26, s0
	v_cndmask_b32_e64 v17, 0, v8, s[86:87]
	v_cvt_pk_bf16_f32 v8, v18, s0
	v_cndmask_b32_e64 v18, v8, 0, s[12:13]
	v_cvt_pk_bf16_f32 v8, v27, s0
	v_cndmask_b32_e64 v16, 0, v22, s[86:87]
	v_cndmask_b32_e64 v21, 0, v23, s[14:15]
	v_cndmask_b32_e64 v22, 0, v8, s[14:15]
	v_cvt_pk_bf16_f32 v8, v19, s0
	ds_write2_b32 v116, v16, v21 offset0:136 offset1:204
	v_cndmask_b32_e64 v16, v8, 0, s[16:17]
	v_add_u32_e32 v8, s91, v79
	ds_write_b16 v8, v10 offset:64512
	ds_write_b16 v8, v20 offset:64656
	ds_write_b16 v8, v17 offset:64800
	ds_write_b16 v8, v22 offset:64944
	v_cvt_pk_bf16_f32 v10, v11, s0
	v_add_u32_e32 v11, s91, v80
	v_cvt_pk_bf16_f32 v9, v9, s0
	ds_write_b16 v11, v9 offset:144
	v_cvt_pk_bf16_f32 v9, v14, s0
	ds_write_b16 v11, v9 offset:288
	v_cvt_pk_bf16_f32 v9, v15, s0
	ds_write_b16 v11, v9 offset:432
	v_add_u32_e32 v9, s91, v81
	v_mfma_f32_16x16x32_bf16 v[28:31], v[40:43], v[44:47], v[28:31]
	ds_write_b16 v11, v10
	ds_write_b16 v9, v12
	ds_write_b16 v9, v13 offset:144
	ds_write_b16 v9, v18 offset:288
	ds_write_b16 v9, v16 offset:432
	v_cndmask_b32_e64 v9, 0, v36, s[18:19]
	v_cndmask_b32_e64 v12, v37, 0, s[20:21]
	ds_write2_b32 v117, v9, v12 offset1:68
	v_cvt_pk_bf16_f32 v9, v33, s0
	v_cndmask_b32_e64 v13, v9, 0, s[22:23]
	v_cndmask_b32_e64 v9, 0, v38, s[24:25]
	v_cndmask_b32_e64 v16, 0, v39, s[28:29]
	v_cvt_pk_bf16_f32 v4, v4, s0
	v_cvt_pk_bf16_f32 v5, v5, s0
	ds_write2_b32 v117, v9, v16 offset0:136 offset1:204
	v_cvt_pk_bf16_f32 v9, v35, s0
	v_cndmask_b32_e64 v4, 0, v4, s[18:19]
	v_cndmask_b32_e64 v11, v28, 0, s[20:21]
	v_cndmask_b32_e64 v5, v5, 0, s[20:21]
	v_cvt_pk_bf16_f32 v6, v6, s0
	v_cvt_pk_bf16_f32 v7, v7, s0
	v_cndmask_b32_e64 v17, v9, 0, s[30:31]
	v_add_u32_e32 v9, s89, v79
	v_cndmask_b32_e64 v12, v29, 0, s[22:23]
	v_cndmask_b32_e64 v6, 0, v6, s[24:25]
	v_cndmask_b32_e64 v7, 0, v7, s[28:29]
	ds_write_b16 v9, v4 offset:64512
	ds_write_b16 v9, v5 offset:64656
	ds_write_b16 v9, v6 offset:64800
	ds_write_b16 v9, v7 offset:64944
	v_cvt_pk_bf16_f32 v4, v11, s0
	v_add_u32_e32 v5, s89, v80
	v_cndmask_b32_e64 v15, v30, 0, s[26:27]
	ds_write_b16 v5, v4
	v_cvt_pk_bf16_f32 v4, v12, s0
	v_cndmask_b32_e64 v16, v31, 0, s[30:31]
	ds_write_b16 v5, v4 offset:144
	v_cvt_pk_bf16_f32 v4, v15, s0
	v_cvt_pk_bf16_f32 v10, v32, s0
	ds_write_b16 v5, v4 offset:288
	v_cvt_pk_bf16_f32 v4, v16, s0
	v_cndmask_b32_e64 v10, v10, 0, s[20:21]
	v_cvt_pk_bf16_f32 v14, v34, s0
	ds_write_b16 v5, v4 offset:432
	v_add_u32_e32 v4, s89, v81
	v_cndmask_b32_e64 v14, v14, 0, s[26:27]
	ds_write_b16 v4, v10
	ds_write_b16 v4, v13 offset:144
	ds_write_b16 v4, v14 offset:288
	ds_write_b16 v4, v17 offset:432
	s_waitcnt lgkmcnt(0)
	s_barrier
	s_cbranch_vccnz .LBB0_756
; #define LAS __attribute__((address_space(3)))
; __device__ __forceinline__ void rwkvA_phase(const Frame& F, int l) {
;     ...
;         if (F.wave == 0) {
;             float t[16];
; #pragma unroll
;             for (int i = 0; i < 16; ++i) {
;                 float acc = (i == qi) ? 1.f : 0.f;
;                 f32x4 ar[4];
; #pragma unroll
;                 for (int q = 0; q < (i + 3) / 4; ++q) ar[q] = *(const LAS f32x4*)(Af + (16 * g + i) * CF + 16 * g + 4 * q);
; #pragma unroll
;                 for (int j = 0; j < i; ++j) acc -= ar[j >> 2][j & 3] * t[j];
;                 t[i] = acc;
;             }
; #pragma unroll
;             for (int i = 0; i < 16; ++i) Tf[(16 * g + i) * CF + 16 * g + qi] = t[i];
;         }
	v_add_u32_e32 v192, v82, v86
	v_add_u32_e32 v193, v82, v102
	ds_read_b128 v[36:39], v192 offset:272
	ds_read_b128 v[40:43], v192 offset:544
	ds_read_b128 v[44:47], v192 offset:816
	ds_read_b128 v[48:51], v192 offset:1088
	ds_read_b128 v[52:55], v192 offset:1360
	ds_read_b128 v[168:171], v192 offset:1632
	ds_read_b128 v[172:175], v192 offset:1904
	ds_read_b128 v[176:179], v192 offset:2176
	ds_read_b128 v[206:209], v192 offset:2448
	ds_read_b128 v[210:213], v192 offset:2720
	ds_read_b128 v[220:223], v192 offset:2992
	ds_read_b128 v[230:233], v192 offset:3264
	ds_read_b128 v[180:183], v192 offset:1376
	ds_read_b128 v[184:187], v192 offset:1648
	ds_read_b128 v[188:191], v192 offset:1920
	ds_read_b128 v[202:205], v192 offset:2192
	ds_read_b128 v[234:237], v192 offset:2464
	ds_read_b128 v[238:241], v192 offset:2736
	ds_read_b128 v[242:245], v192 offset:3008
	ds_read_b128 v[246:249], v192 offset:3280
	ds_read_b128 v[10:13], v192 offset:2480
	ds_read_b128 v[14:17], v192 offset:2752
	ds_read_b128 v[18:21], v192 offset:3024
	ds_read_b128 v[4:7], v192 offset:3296
	s_waitcnt lgkmcnt(12)
	v_fma_f32 v23, -v84, v36, v85
	v_fma_f32 v24, -v84, v40, v87
	v_fma_f32 v25, -v84, v44, v88
	v_fma_f32 v26, -v84, v48, v89
	v_fma_f32 v27, -v84, v52, v90
	v_fma_f32 v28, -v84, v168, v92
	v_fma_f32 v29, -v84, v172, v93
	v_fma_f32 v30, -v84, v176, v94
	v_fma_f32 v31, -v84, v206, v95
	v_fma_f32 v32, -v84, v210, v96
	v_fma_f32 v33, -v84, v220, v97
	v_fma_f32 v34, -v84, v230, v98
	v_fma_f32 v24, -v23, v41, v24
	v_fma_f32 v25, -v23, v45, v25
	v_fma_f32 v26, -v23, v49, v26
	v_fma_f32 v27, -v23, v53, v27
	v_fma_f32 v28, -v23, v169, v28
	v_fma_f32 v29, -v23, v173, v29
	v_fma_f32 v30, -v23, v177, v30
	v_fma_f32 v31, -v23, v207, v31
	v_fma_f32 v32, -v23, v211, v32
	v_fma_f32 v33, -v23, v221, v33
	v_fma_f32 v34, -v23, v231, v34
	v_fma_f32 v25, -v24, v46, v25
	v_fma_f32 v26, -v24, v50, v26
	v_fma_f32 v27, -v24, v54, v27
	v_fma_f32 v28, -v24, v170, v28
	v_fma_f32 v29, -v24, v174, v29
	v_fma_f32 v30, -v24, v178, v30
	v_fma_f32 v31, -v24, v208, v31
	v_fma_f32 v32, -v24, v212, v32
	v_fma_f32 v33, -v24, v222, v33
	v_fma_f32 v34, -v24, v232, v34
	v_fma_f32 v26, -v25, v51, v26
	v_fma_f32 v27, -v25, v55, v27
	v_fma_f32 v28, -v25, v171, v28
	v_fma_f32 v29, -v25, v175, v29
	v_fma_f32 v30, -v25, v179, v30
	v_fma_f32 v31, -v25, v209, v31
	v_fma_f32 v32, -v25, v213, v32
	v_fma_f32 v33, -v25, v223, v33
	v_fma_f32 v34, -v25, v233, v34
	s_waitcnt lgkmcnt(4)
	v_fma_f32 v27, -v26, v180, v27
	v_fma_f32 v28, -v26, v184, v28
	v_fma_f32 v29, -v26, v188, v29
	v_fma_f32 v30, -v26, v202, v30
	v_fma_f32 v31, -v26, v234, v31
	v_fma_f32 v32, -v26, v238, v32
	v_fma_f32 v33, -v26, v242, v33
	v_fma_f32 v34, -v26, v246, v34
	v_fma_f32 v28, -v27, v185, v28
	v_fma_f32 v29, -v27, v189, v29
	v_fma_f32 v30, -v27, v203, v30
	v_fma_f32 v31, -v27, v235, v31
	v_fma_f32 v32, -v27, v239, v32
	v_fma_f32 v33, -v27, v243, v33
	v_fma_f32 v34, -v27, v247, v34
	v_fma_f32 v29, -v28, v190, v29
	v_fma_f32 v30, -v28, v204, v30
	v_fma_f32 v31, -v28, v236, v31
	v_fma_f32 v32, -v28, v240, v32
	v_fma_f32 v33, -v28, v244, v33
	v_fma_f32 v34, -v28, v248, v34
	v_fma_f32 v30, -v29, v205, v30
	v_fma_f32 v31, -v29, v237, v31
	v_fma_f32 v32, -v29, v241, v32
	v_fma_f32 v33, -v29, v245, v33
	v_fma_f32 v34, -v29, v249, v34
	ds_read_b128 v[36:39], v192 offset:3536
	ds_read_b128 v[40:43], v192 offset:3808
	ds_read_b128 v[44:47], v193
	ds_read_b128 v[48:51], v192 offset:3552
	ds_read_b128 v[52:55], v192 offset:3824
	ds_read_b128 v[168:171], v193 offset:16
	ds_read_b128 v[172:175], v192 offset:3568
	ds_read_b128 v[176:179], v192 offset:3840
	ds_read_b128 v[180:183], v193 offset:32
	ds_read_b128 v[184:187], v192 offset:3584
	ds_read_b128 v[188:191], v192 offset:3856
	ds_read_b128 v[202:205], v193 offset:48
	s_waitcnt lgkmcnt(12)
	v_fma_f32 v31, -v30, v10, v31
	v_fma_f32 v32, -v30, v14, v32
	v_fma_f32 v33, -v30, v18, v33
	v_fma_f32 v34, -v30, v4, v34
	v_fma_f32 v32, -v31, v15, v32
	v_fma_f32 v33, -v31, v19, v33
	v_fma_f32 v34, -v31, v5, v34
	v_fma_f32 v33, -v32, v20, v33
	v_fma_f32 v34, -v32, v6, v34
	v_fma_f32 v34, -v33, v7, v34
	s_waitcnt lgkmcnt(9)
	v_fma_f32 v35, -v84, v36, v99
	v_fma_f32 v22, -v84, v40, v100
	v_fma_f32 v4, -v84, v44, v101
	v_fma_f32 v35, -v23, v37, v35
	v_fma_f32 v22, -v23, v41, v22
	v_fma_f32 v4, -v23, v45, v4
	v_fma_f32 v35, -v24, v38, v35
	v_fma_f32 v22, -v24, v42, v22
	v_fma_f32 v4, -v24, v46, v4
	v_fma_f32 v35, -v25, v39, v35
	v_fma_f32 v22, -v25, v43, v22
	v_fma_f32 v4, -v25, v47, v4
	s_waitcnt lgkmcnt(6)
	v_fma_f32 v35, -v26, v48, v35
	v_fma_f32 v22, -v26, v52, v22
	v_fma_f32 v4, -v26, v168, v4
	v_fma_f32 v35, -v27, v49, v35
	v_fma_f32 v22, -v27, v53, v22
	v_fma_f32 v4, -v27, v169, v4
	v_fma_f32 v35, -v28, v50, v35
	v_fma_f32 v22, -v28, v54, v22
	v_fma_f32 v4, -v28, v170, v4
	v_fma_f32 v35, -v29, v51, v35
	v_fma_f32 v22, -v29, v55, v22
	v_fma_f32 v4, -v29, v171, v4
	s_waitcnt lgkmcnt(3)
	v_fma_f32 v35, -v30, v172, v35
	v_fma_f32 v22, -v30, v176, v22
	v_fma_f32 v4, -v30, v180, v4
	v_fma_f32 v35, -v31, v173, v35
	v_fma_f32 v22, -v31, v177, v22
	v_fma_f32 v4, -v31, v181, v4
	v_fma_f32 v35, -v32, v174, v35
	v_fma_f32 v22, -v32, v178, v22
	v_fma_f32 v4, -v32, v182, v4
	v_fma_f32 v35, -v33, v175, v35
	v_fma_f32 v22, -v33, v179, v22
	v_fma_f32 v4, -v33, v183, v4
	s_waitcnt lgkmcnt(0)
	v_fma_f32 v35, -v34, v184, v35
	v_fma_f32 v22, -v34, v188, v22
	v_fma_f32 v4, -v34, v202, v4
	v_fma_f32 v22, -v35, v189, v22
	v_fma_f32 v4, -v35, v203, v4
	v_fma_f32 v4, -v22, v204, v4
	v_add_u32_e32 v5, v83, v86
	v_add_u32_e32 v6, 0x400, v5
	ds_write2_b32 v5, v84, v23 offset1:68
	ds_write2_b32 v5, v24, v25 offset0:136 offset1:204
	ds_write2_b32 v6, v26, v27 offset0:16 offset1:84
	ds_write2_b32 v6, v28, v29 offset0:152 offset1:220
	v_add_u32_e32 v6, 0x800, v5
	ds_write2_b32 v6, v30, v31 offset0:32 offset1:100
	ds_write2_b32 v6, v32, v33 offset0:168 offset1:236
	v_add_u32_e32 v6, 0xc00, v5
	ds_write2_b32 v6, v34, v35 offset0:48 offset1:116
	ds_write_b32 v5, v22 offset:3808
	v_add_u32_e32 v5, v83, v102
	ds_write_b32 v5, v4

; __device__ __forceinline__ void lds_barrier() { asm volatile("s_waitcnt lgkmcnt(0)\n\ts_barrier" ::: "memory"); }
; #define MFMA_BF(a, b, c) __builtin_amdgcn_mfma_f32_16x16x32_bf16(a, b, c, 0, 0, 0)
; __device__ __forceinline__ void rwkvA_phase(const Frame& F, int l) {
;     ...
;         const int hd = task / CH_NCH, c = task - hd * CH_NCH, head = hd >> 1, dir = hd & 1;
;         const int ch = head * 64 + F.lane;
;         const float kkc = F.in[I_KK][(size_t)l * AW + ch], kac = F.in[I_KA][(size_t)l * AW + ch];
;     ...
;         {
;             f32x4 av[2] = {z4, z4}, p[2] = {z4, z4};
; #pragma unroll
;             for (int ks = 0; ks < 2; ++ks) {
;                 const bf16x8 aA = ch_rowread(L + O_AAK, tr, ks, qi, g), aT = ch_rowread(L + O_T, tr, ks, qi, g);
; #pragma unroll
;                 for (int t = 0; t < 2; ++t) { av[t] = MFMA_BF(aA, ch_trread(L + O_V, tcb + t, ks, qi, g), av[t]); p[t] = MFMA_BF(aT, ch_trread(L + O_KT, tcb + t, ks, qi, g), p[t]); }
;             }
; #pragma unroll
;             for (int t = 0; t < 2; ++t) { ch_store_bf16(L + O_BB, tr, tcb + t, qi, g, av[t]); ch_store_bf16(L + O_KB, tr, tcb + t, qi, g, p[t]); }
;         }
;         lds_barrier();
;         {
;             f32x4 q[2] = {z4, z4};
; #pragma unroll
;             for (int ks = 0; ks < 2; ++ks) {
;                 const bf16x8 aT = ch_rowread(L + O_T, tr, ks, qi, g);
; #pragma unroll
;                 for (int t = 0; t < 2; ++t) q[t] = MFMA_BF(aT, ch_trread(L + O_BB, tcb + t, ks, qi, g), q[t]);
;             }
; #pragma unroll
;             for (int t = 0; t < 2; ++t) ch_store_bf16(L + O_AAK, tr, tcb + t, qi, g, q[t]);
;         }
;         lds_barrier();
.LBB0_767:
	s_or_b64 exec, exec, s[68:69]
	s_waitcnt lgkmcnt(0)
	s_barrier
	ds_read_b128 v[4:7], v125 offset:64512
	v_add_u32_e32 v16, s91, v103
	v_add_u32_e32 v69, s89, v103
	ds_read_b64_tr_b16 v[10:11], v16 offset:36864
	ds_read_b64_tr_b16 v[12:13], v16 offset:37440
	ds_read_b128 v[18:21], v118
	ds_read_b64_tr_b16 v[22:23], v16
	ds_read_b64_tr_b16 v[24:25], v16 offset:576
	ds_read_b64_tr_b16 v[26:27], v69 offset:36864
	ds_read_b64_tr_b16 v[28:29], v69 offset:37440
	s_waitcnt lgkmcnt(2)
	v_mfma_f32_16x16x32_bf16 v[22:25], v[18:21], v[22:25], v[0:3]
	v_add_u32_e32 v129, s91, v104
	v_add_u32_e32 v130, s89, v104
	v_readlane_b32 s8, v255, 24
	v_mfma_f32_16x16x32_bf16 v[10:13], v[4:7], v[10:13], v[0:3]
	v_readlane_b32 s9, v255, 25
	s_waitcnt lgkmcnt(0)
	v_mfma_f32_16x16x32_bf16 v[4:7], v[4:7], v[26:29], v[0:3]
	ds_read_b64_tr_b16 v[26:27], v69
	ds_read_b64_tr_b16 v[28:29], v69 offset:576
	ds_read_b128 v[30:33], v125 offset:64576
	s_waitcnt lgkmcnt(1)
	v_mfma_f32_16x16x32_bf16 v[18:21], v[18:21], v[26:29], v[0:3]
	ds_read_b64_tr_b16 v[26:27], v16 offset:41472
	ds_read_b64_tr_b16 v[28:29], v16 offset:42048
	ds_read_b128 v[34:37], v118 offset:64
	s_waitcnt lgkmcnt(1)
	v_mfma_f32_16x16x32_bf16 v[10:13], v[30:33], v[26:29], v[10:13]
	ds_read_b64_tr_b16 v[26:27], v16 offset:4608
	ds_read_b64_tr_b16 v[28:29], v16 offset:5184
	s_waitcnt lgkmcnt(0)
	v_mfma_f32_16x16x32_bf16 v[22:25], v[34:37], v[26:29], v[22:25]
	ds_read_b64_tr_b16 v[26:27], v69 offset:41472
	ds_read_b64_tr_b16 v[28:29], v69 offset:42048
	s_nop 1
	v_cvt_pk_bf16_f32 v10, v10, s0
	s_waitcnt lgkmcnt(0)
	v_mfma_f32_16x16x32_bf16 v[4:7], v[30:33], v[26:29], v[4:7]
	ds_read_b64_tr_b16 v[26:27], v69 offset:4608
	ds_read_b64_tr_b16 v[28:29], v69 offset:5184
	ds_write_b16 v8, v10 offset:46080
	v_cvt_pk_bf16_f32 v10, v11, s0
	s_waitcnt lgkmcnt(1)
	v_mfma_f32_16x16x32_bf16 v[18:21], v[34:37], v[26:29], v[18:21]
	s_nop 1
	v_cvt_pk_bf16_f32 v4, v4, s0
	ds_write_b16 v9, v4 offset:46080
	v_cvt_pk_bf16_f32 v4, v5, s0
	ds_write_b16 v8, v10 offset:46224
	v_cvt_pk_bf16_f32 v10, v12, s0
	ds_write_b16 v9, v4 offset:46224
	v_cvt_pk_bf16_f32 v4, v6, s0
	ds_write_b16 v8, v10 offset:46368
	v_cvt_pk_bf16_f32 v10, v13, s0
	ds_write_b16 v9, v4 offset:46368
	v_cvt_pk_bf16_f32 v4, v7, s0
	ds_write_b16 v8, v10 offset:46512
	v_cvt_pk_bf16_f32 v10, v22, s0
	ds_write_b16 v9, v4 offset:46512
	v_cvt_pk_bf16_f32 v4, v18, s0
	ds_write_b16 v8, v10 offset:55296
	v_cvt_pk_bf16_f32 v10, v23, s0
	ds_write_b16 v9, v4 offset:55296
	v_cvt_pk_bf16_f32 v4, v19, s0
	ds_write_b16 v8, v10 offset:55440
	v_cvt_pk_bf16_f32 v10, v24, s0
	ds_write_b16 v9, v4 offset:55440
	v_cvt_pk_bf16_f32 v4, v20, s0
	ds_write_b16 v8, v10 offset:55584
	v_cvt_pk_bf16_f32 v10, v25, s0
	ds_write_b16 v9, v4 offset:55584
	v_cvt_pk_bf16_f32 v4, v21, s0
	ds_write_b16 v8, v10 offset:55728
	ds_write_b16 v9, v4 offset:55728
	s_waitcnt lgkmcnt(0)
	s_barrier
	ds_read_b128 v[4:7], v118
	ds_read_b64_tr_b16 v[10:11], v16 offset:46080
	ds_read_b64_tr_b16 v[12:13], v16 offset:46656
	ds_read_b64_tr_b16 v[18:19], v69 offset:46080
	ds_read_b64_tr_b16 v[20:21], v69 offset:46656
	ds_read_b128 v[22:25], v118 offset:64
	s_waitcnt lgkmcnt(3)
	v_mfma_f32_16x16x32_bf16 v[10:13], v[4:7], v[10:13], v[0:3]
	s_waitcnt lgkmcnt(1)
	v_mfma_f32_16x16x32_bf16 v[4:7], v[4:7], v[18:21], v[0:3]
	ds_read_b64_tr_b16 v[18:19], v16 offset:50688
	ds_read_b64_tr_b16 v[20:21], v16 offset:51264
	s_waitcnt lgkmcnt(0)
	v_mfma_f32_16x16x32_bf16 v[10:13], v[22:25], v[18:21], v[10:13]
	ds_read_b64_tr_b16 v[18:19], v69 offset:50688
	ds_read_b64_tr_b16 v[20:21], v69 offset:51264
	s_waitcnt lgkmcnt(0)
	v_mfma_f32_16x16x32_bf16 v[4:7], v[22:25], v[18:21], v[4:7]
	s_nop 3
	v_cvt_pk_bf16_f32 v10, v10, s0
	ds_write_b16 v8, v10 offset:64512
	v_cvt_pk_bf16_f32 v10, v11, s0
	s_nop 0
	v_cvt_pk_bf16_f32 v4, v4, s0
	ds_write_b16 v9, v4 offset:64512
	v_cvt_pk_bf16_f32 v4, v5, s0
	ds_write_b16 v8, v10 offset:64656
	v_cvt_pk_bf16_f32 v10, v12, s0
	ds_write_b16 v9, v4 offset:64656
	v_cvt_pk_bf16_f32 v4, v6, s0
	ds_write_b16 v8, v10 offset:64800
	v_cvt_pk_bf16_f32 v10, v13, s0
	ds_write_b16 v9, v4 offset:64800
	v_cvt_pk_bf16_f32 v4, v7, s0
	ds_write_b16 v8, v10 offset:64944
	ds_write_b16 v9, v4 offset:64944
	s_waitcnt lgkmcnt(0)
	s_barrier
	s_waitcnt vmcnt(0)
	s_cmp_ge_i32 s42, s85
	s_cbranch_scc1 .Lmy_pf_skip
	s_mul_hi_i32 s36, s42, 0x3e0f83e1
	s_lshr_b32 s37, s36, 31
	s_ashr_i32 s36, s36, 5
	s_add_i32 s37, s36, s37
	s_lshl_b32 s36, s37, 5
	s_andn2_b32 s36, s36, 63
	v_add_u32_e32 v202, s36, v198
	v_readlane_b32 s38, v255, 14
	v_ashrrev_i32_e32 v203, 31, v202
	v_readlane_b32 s39, v255, 15
	v_readlane_b32 s40, v253, 56
	v_readlane_b32 s41, v253, 57
	s_nop 1
	v_lshl_add_u64 v[202:203], v[202:203], 0, s[38:39]
	v_lshlrev_b64 v[202:203], 2, v[202:203]
	v_lshl_add_u64 v[204:205], s[40:41], 0, v[202:203]
	global_load_dword v250, v[204:205], off
	v_readlane_b32 s40, v253, 58
	v_readlane_b32 s41, v253, 59
	s_nop 1
	v_lshl_add_u64 v[202:203], s[40:41], 0, v[202:203]
	global_load_dword v251, v[202:203], off

; __device__ __forceinline__ void unpack8(const u32x4 w, float (&f)[8]) { f[0] = bflo(w.x); f[1] = bfhi(w.x); f[2] = bflo(w.y); f[3] = bfhi(w.y); f[4] = bflo(w.z); f[5] = bfhi(w.z); f[6] = bflo(w.w); f[7] = bfhi(w.w); }
; __device__ __forceinline__ u32x4 pack8(const float (&f)[8]) { u32x4 w; w.x = cvt_pk_bf16(f[0], f[1]); w.y = cvt_pk_bf16(f[2], f[3]); w.z = cvt_pk_bf16(f[4], f[5]); w.w = cvt_pk_bf16(f[6], f[7]); return w; }
; __device__ __forceinline__ void lds_barrier() { asm volatile("s_waitcnt lgkmcnt(0)\n\ts_barrier" ::: "memory"); }
; __device__ __forceinline__ void mla_unit(const Frame& F, int h, int q0, int key0, int ntiles, int mode, int su) {
;     ...
;     bf16x8 Qf[12];
;     {
;         const bf16_t* qp = Q + (size_t)qr * 1536 + h * QHD;
; #pragma unroll
;         for (int ks = 0; ks < 8; ++ks) { float x[8]; unpack8(*(const u32x4*)(qp + 16 * ks + 8 * hh), x);
; #pragma unroll
;             for (int j = 0; j < 8; ++j) x[j] *= SC;
;             Qf[ks] = __builtin_bit_cast(bf16x8, pack8(x)); }
; #pragma unroll
;         for (int ks = 8; ks < 12; ++ks) {
;             const int d0 = 16 * ks + 8 * hh;
;             const u32x4 own = *(const u32x4*)(qp + d0);
;             if (qr < SEQ) {
;                 const u32x4 par = *(const u32x4*)(qp + d0 + ((ks & 1) ? -16 : 16));
;                 float xo[8], xp[8], o[8]; unpack8(own, xo); unpack8(par, xp);
;                 const float* rp = rope + ((size_t)qr * 32 + ((ks - 8) >> 1) * 16 + 8 * hh) * 2;
; #pragma unroll
;                 for (int j = 0; j < 8; ++j) { const float cs = rp[2 * j], sn = rp[2 * j + 1]; o[j] = SC * ((ks & 1) ? (xp[j] * sn + xo[j] * cs) : (xo[j] * cs - xp[j] * sn)); }
;                 Qf[ks] = __builtin_bit_cast(bf16x8, pack8(o));
;             } else { float x[8]; unpack8(own, x);
; #pragma unroll
;                 for (int j = 0; j < 8; ++j) x[j] *= SC;
;                 Qf[ks] = __builtin_bit_cast(bf16x8, pack8(x)); }
;         }
;     }
;     ...
;     asm volatile("s_waitcnt vmcnt(0)" ::: "memory");
;     lds_barrier();
;     const int krd = ql * MA_KSTR + 16 * hh;
;     const int vrd = (4 * hh + ((F.lane & 15) >> 2)) * MA_VSTR + (((F.lane >> 4) & 1) * 16 + (F.lane & 3) * 4) * 2;
.LBB0_884:
	s_mov_b32 s14, 0x3dd53b94
	v_pk_mul_f32 v[96:97], v[96:97], s[14:15] op_sel_hi:[1,0]
	v_pk_mul_f32 v[98:99], v[98:99], s[14:15] op_sel_hi:[1,0]
	v_cvt_pk_bf16_f32 v145, v96, v97
	v_pk_mul_f32 v[96:97], v[106:107], s[14:15] op_sel_hi:[1,0]
	v_cvt_pk_bf16_f32 v146, v98, v99
	v_cvt_pk_bf16_f32 v150, v96, v97
	v_lshlrev_b32_e32 v96, 16, v92
	v_and_b32_e32 v97, 0xffff0000, v92
	v_lshlrev_b32_e32 v92, 16, v93
	v_and_b32_e32 v93, 0xffff0000, v93
	v_pk_mul_f32 v[92:93], v[92:93], s[14:15] op_sel_hi:[1,0]
	v_pk_mul_f32 v[98:99], v[104:105], s[14:15] op_sel_hi:[1,0]
	v_cvt_pk_bf16_f32 v153, v92, v93
	v_lshlrev_b32_e32 v92, 16, v88
	v_and_b32_e32 v93, 0xffff0000, v88
	v_lshlrev_b32_e32 v88, 16, v89
	v_and_b32_e32 v89, 0xffff0000, v89
	v_pk_mul_f32 v[88:89], v[88:89], s[14:15] op_sel_hi:[1,0]
	v_cvt_pk_bf16_f32 v149, v98, v99
	v_cvt_pk_bf16_f32 v157, v88, v89
	v_lshlrev_b32_e32 v88, 16, v84
	v_and_b32_e32 v89, 0xffff0000, v84
	v_lshlrev_b32_e32 v84, 16, v85
	v_and_b32_e32 v85, 0xffff0000, v85
	v_pk_mul_f32 v[84:85], v[84:85], s[14:15] op_sel_hi:[1,0]
	v_lshlrev_b32_e32 v98, 16, v94
	v_and_b32_e32 v99, 0xffff0000, v94
	v_lshlrev_b32_e32 v94, 16, v95
	v_and_b32_e32 v95, 0xffff0000, v95
	v_cvt_pk_bf16_f32 v161, v84, v85
	v_lshlrev_b32_e32 v84, 16, v80
	v_and_b32_e32 v85, 0xffff0000, v80
	v_lshlrev_b32_e32 v80, 16, v81
	v_and_b32_e32 v81, 0xffff0000, v81
	v_pk_mul_f32 v[94:95], v[94:95], s[14:15] op_sel_hi:[1,0]
	v_pk_mul_f32 v[80:81], v[80:81], s[14:15] op_sel_hi:[1,0]
	v_cvt_pk_bf16_f32 v155, v94, v95
	v_lshlrev_b32_e32 v94, 16, v90
	v_and_b32_e32 v95, 0xffff0000, v90
	v_lshlrev_b32_e32 v90, 16, v91
	v_and_b32_e32 v91, 0xffff0000, v91
	v_cvt_pk_bf16_f32 v165, v80, v81
	v_lshlrev_b32_e32 v80, 16, v76
	v_and_b32_e32 v81, 0xffff0000, v76
	v_lshlrev_b32_e32 v76, 16, v77
	v_and_b32_e32 v77, 0xffff0000, v77
	v_pk_mul_f32 v[90:91], v[90:91], s[14:15] op_sel_hi:[1,0]
	v_pk_mul_f32 v[76:77], v[76:77], s[14:15] op_sel_hi:[1,0]
	v_cvt_pk_bf16_f32 v159, v90, v91
	v_lshlrev_b32_e32 v90, 16, v86
	v_and_b32_e32 v91, 0xffff0000, v86
	v_lshlrev_b32_e32 v86, 16, v87
	v_and_b32_e32 v87, 0xffff0000, v87
	v_cvt_pk_bf16_f32 v169, v76, v77
	v_lshlrev_b32_e32 v76, 16, v72
	v_and_b32_e32 v77, 0xffff0000, v72
	v_lshlrev_b32_e32 v72, 16, v73
	v_and_b32_e32 v73, 0xffff0000, v73
	v_pk_mul_f32 v[86:87], v[86:87], s[14:15] op_sel_hi:[1,0]
	v_pk_mul_f32 v[72:73], v[72:73], s[14:15] op_sel_hi:[1,0]
	v_cvt_pk_bf16_f32 v163, v86, v87
	v_lshlrev_b32_e32 v86, 16, v82
	v_and_b32_e32 v87, 0xffff0000, v82
	v_lshlrev_b32_e32 v82, 16, v83
	v_and_b32_e32 v83, 0xffff0000, v83
	v_cvt_pk_bf16_f32 v173, v72, v73
	v_lshlrev_b32_e32 v72, 16, v68
	v_and_b32_e32 v73, 0xffff0000, v68
	v_lshlrev_b32_e32 v68, 16, v69
	v_and_b32_e32 v69, 0xffff0000, v69
	v_pk_mul_f32 v[82:83], v[82:83], s[14:15] op_sel_hi:[1,0]
	v_pk_mul_f32 v[68:69], v[68:69], s[14:15] op_sel_hi:[1,0]
	v_cvt_pk_bf16_f32 v167, v82, v83
	v_lshlrev_b32_e32 v82, 16, v78
	v_and_b32_e32 v83, 0xffff0000, v78
	v_lshlrev_b32_e32 v78, 16, v79
	v_and_b32_e32 v79, 0xffff0000, v79
	v_cvt_pk_bf16_f32 v177, v68, v69
	v_lshlrev_b32_e32 v68, 16, v64
	v_and_b32_e32 v69, 0xffff0000, v64
	v_lshlrev_b32_e32 v64, 16, v65
	v_and_b32_e32 v65, 0xffff0000, v65
	v_mul_f32_e32 v102, 0x3dd53b94, v121
	s_and_b64 s[8:9], s[0:1], exec
	v_pk_mul_f32 v[78:79], v[78:79], s[14:15] op_sel_hi:[1,0]
	v_pk_mul_f32 v[64:65], v[64:65], s[14:15] op_sel_hi:[1,0]
	v_cvt_pk_bf16_f32 v139, v140, v102
	v_mul_f32_e32 v102, 0x3dd53b94, v113
	v_cvt_pk_bf16_f32 v171, v78, v79
	v_lshlrev_b32_e32 v78, 16, v74
	v_and_b32_e32 v79, 0xffff0000, v74
	v_lshlrev_b32_e32 v74, 16, v75
	v_and_b32_e32 v75, 0xffff0000, v75
	v_cvt_pk_bf16_f32 v181, v64, v65
	v_lshlrev_b32_e32 v64, 4, v131
	s_movk_i32 s8, 0x190
	v_cvt_pk_bf16_f32 v143, v126, v102
	v_mul_f32_e32 v102, 0x3dd53b94, v103
	v_pk_mul_f32 v[74:75], v[74:75], s[14:15] op_sel_hi:[1,0]
	s_waitcnt vmcnt(0)
	v_mad_u32_u24 v212, v129, s8, v64
	v_cvt_pk_bf16_f32 v147, v112, v102
	v_pk_mul_f32 v[100:101], v[100:101], s[14:15] op_sel_hi:[1,0]
	v_mul_f32_e32 v102, 0x3dd53b94, v109
	v_pk_mul_f32 v[98:99], v[98:99], s[14:15] op_sel_hi:[1,0]
	v_cvt_pk_bf16_f32 v175, v74, v75
	v_lshlrev_b32_e32 v74, 16, v70
	v_and_b32_e32 v75, 0xffff0000, v70
	v_lshlrev_b32_e32 v70, 16, v71
	v_and_b32_e32 v71, 0xffff0000, v71
	s_waitcnt lgkmcnt(0)
	s_barrier
; #define LAS __attribute__((address_space(3)))
; #define MFMA32(a, b, c) __builtin_amdgcn_mfma_f32_32x32x16_bf16(a, b, c, 0, 0, 0)
; __device__ __forceinline__ void mla_unit(const Frame& F, int h, int q0, int key0, int ntiles, int mode, int su) {
;     ...
;     {   const LAS unsigned char* kb = F.lds + MA_K_OFF + krd;
; #pragma unroll
;         for (int kt = 0; kt < 2; ++kt) { { const float nm = -m;
; #pragma unroll
;             for (int r = 0; r < 16; ++r) sA[kt][r] = nm; }
; #pragma unroll
;             for (int ks = 0; ks < 12; ++ks) { const bf16x8 kf = *(const LAS bf16x8*)(kb + kt * 32 * MA_KSTR + ks * 32); sA[kt] = MFMA32(kf, Qf[ks], sA[kt]); } } }
;     int c0 = 0, c1 = 1, c2 = 2;
;     static_assert(((SEQ + CTXL) / 64) % 2 == 0, "tile loop is unrolled by two");
	v_add_u32_e32 v213, 0, v212
	v_cvt_pk_bf16_f32 v148, v100, v101
	v_cvt_pk_bf16_f32 v151, v108, v102
	v_pk_mul_f32 v[96:97], v[96:97], s[14:15] op_sel_hi:[1,0]
	v_cvt_pk_bf16_f32 v154, v98, v99
	v_pk_mul_f32 v[70:71], v[70:71], s[14:15] op_sel_hi:[1,0]
	v_lshlrev_b32_e32 v204, 2, v131
	v_lshrrev_b32_e32 v64, 2, v198
	ds_read_b128 v[98:101], v213
	ds_read_b128 v[102:105], v213 offset:32
	v_cvt_pk_bf16_f32 v152, v96, v97
	v_cvt_pk_bf16_f32 v179, v70, v71
	v_lshlrev_b32_e32 v70, 16, v66
	v_and_b32_e32 v71, 0xffff0000, v66
	v_lshlrev_b32_e32 v66, 16, v67
	v_and_b32_e32 v67, 0xffff0000, v67
	v_and_or_b32 v96, v64, 3, v204
	v_and_b32_e32 v64, 16, v198
	v_lshlrev_b32_e32 v65, 2, v198
	v_pk_mul_f32 v[76:77], v[76:77], s[14:15] op_sel_hi:[1,0]
	v_pk_mul_f32 v[78:79], v[78:79], s[14:15] op_sel_hi:[1,0]
	v_pk_mul_f32 v[72:73], v[72:73], s[14:15] op_sel_hi:[1,0]
	v_pk_mul_f32 v[74:75], v[74:75], s[14:15] op_sel_hi:[1,0]
	v_pk_mul_f32 v[68:69], v[68:69], s[14:15] op_sel_hi:[1,0]
	v_pk_mul_f32 v[70:71], v[70:71], s[14:15] op_sel_hi:[1,0]
	v_pk_mul_f32 v[66:67], v[66:67], s[14:15] op_sel_hi:[1,0]
	v_and_or_b32 v97, v65, 12, v64
	s_waitcnt vmcnt(0)
	v_xor_b32_e32 v64, 0x80000000, v199
	v_pk_mul_f32 v[92:93], v[92:93], s[14:15] op_sel_hi:[1,0]
	v_pk_mul_f32 v[94:95], v[94:95], s[14:15] op_sel_hi:[1,0]
	v_pk_mul_f32 v[88:89], v[88:89], s[14:15] op_sel_hi:[1,0]
	v_pk_mul_f32 v[90:91], v[90:91], s[14:15] op_sel_hi:[1,0]
	v_pk_mul_f32 v[84:85], v[84:85], s[14:15] op_sel_hi:[1,0]
	v_pk_mul_f32 v[86:87], v[86:87], s[14:15] op_sel_hi:[1,0]
	v_pk_mul_f32 v[80:81], v[80:81], s[14:15] op_sel_hi:[1,0]
	v_pk_mul_f32 v[82:83], v[82:83], s[14:15] op_sel_hi:[1,0]
	v_cvt_pk_bf16_f32 v172, v76, v77
	v_cvt_pk_bf16_f32 v174, v78, v79
	v_cvt_pk_bf16_f32 v176, v72, v73
	v_cvt_pk_bf16_f32 v178, v74, v75
	v_cvt_pk_bf16_f32 v180, v68, v69
	v_cvt_pk_bf16_f32 v182, v70, v71
	v_cvt_pk_bf16_f32 v183, v66, v67
	v_mov_b32_e32 v65, v64
	v_mov_b32_e32 v66, v64
	v_mov_b32_e32 v67, v64
	v_mov_b32_e32 v68, v64
	v_mov_b32_e32 v69, v64
	v_mov_b32_e32 v70, v64
	v_mov_b32_e32 v71, v64
	v_mov_b32_e32 v72, v64
	v_mov_b32_e32 v73, v64
	v_mov_b32_e32 v74, v64
	v_mov_b32_e32 v75, v64
	v_mov_b32_e32 v76, v64
	v_mov_b32_e32 v77, v64
	v_mov_b32_e32 v78, v64
	v_mov_b32_e32 v79, v64
	v_cvt_pk_bf16_f32 v156, v92, v93
	v_cvt_pk_bf16_f32 v158, v94, v95
	v_cvt_pk_bf16_f32 v160, v88, v89
	v_cvt_pk_bf16_f32 v162, v90, v91
	v_cvt_pk_bf16_f32 v164, v84, v85
	v_cvt_pk_bf16_f32 v166, v86, v87
	v_cvt_pk_bf16_f32 v168, v80, v81
	v_cvt_pk_bf16_f32 v170, v82, v83
	s_waitcnt lgkmcnt(1)
	v_mfma_f32_32x32x16_bf16 v[80:95], v[98:101], v[152:155], v[64:79]
	ds_read_b128 v[98:101], v213 offset:64
	v_mul_f32_e64 v110, v110, s14
	v_mul_f32_e64 v111, v111, s14
	v_mul_f32_e64 v116, v116, s14
	v_mul_f32_e64 v117, v117, s14
	v_cvt_pk_bf16_f32 v144, v110, v111
	v_pk_mul_f32 v[114:115], v[114:115], s[14:15] op_sel_hi:[1,0]
	v_pk_mul_f32 v[136:137], v[136:137], s[14:15] op_sel_hi:[1,0]
	v_cvt_pk_bf16_f32 v138, v116, v117
	s_waitcnt lgkmcnt(1)
	v_mfma_f32_32x32x16_bf16 v[80:95], v[102:105], v[156:159], v[80:95]
	v_cvt_pk_bf16_f32 v136, v136, v137
	v_cvt_pk_bf16_f32 v137, v114, v115
	v_mul_f32_e64 v114, v124, s14
	v_mul_f32_e64 v115, v125, s14
	v_mul_f32_e64 v116, v122, s14
	v_mul_f32_e64 v117, v123, s14
	v_pk_mul_f32 v[118:119], v[118:119], s[14:15] op_sel_hi:[1,0]
	v_cvt_pk_bf16_f32 v141, v116, v117
	v_cvt_pk_bf16_f32 v140, v118, v119
	s_waitcnt lgkmcnt(0)
	v_mfma_f32_32x32x16_bf16 v[80:95], v[98:101], v[160:163], v[80:95]
	ds_read_b128 v[98:101], v213 offset:96
	v_cvt_pk_bf16_f32 v142, v114, v115
	s_movk_i32 s8, 0x140
	s_movk_i32 s3, 0x42
	v_mul_lo_u32 v96, v96, s8
	s_cselect_b32 s3, s3, 0x84
	v_lshl_or_b32 v216, v97, 1, v96
	s_waitcnt lgkmcnt(0)
	v_mfma_f32_32x32x16_bf16 v[80:95], v[98:101], v[164:167], v[80:95]
	ds_read_b128 v[98:101], v213 offset:128
	s_add_i32 s8, 0, 0x12c00
	v_cndmask_b32_e64 v96, 0, -1, s[0:1]
	s_mov_b32 s16, 2
	s_mov_b32 s17, 1
	s_add_i32 s18, s3, -1
	v_add_u32_e32 v229, s8, v216
	s_waitcnt lgkmcnt(0)
	v_mfma_f32_32x32x16_bf16 v[80:95], v[98:101], v[168:171], v[80:95]
	ds_read_b128 v[98:101], v213 offset:160
	s_mov_b32 s0, 0
	v_readfirstlane_b32 s19, v96
	s_mov_b32 s24, 0
	s_waitcnt lgkmcnt(0)
	v_mfma_f32_32x32x16_bf16 v[80:95], v[98:101], v[172:175], v[80:95]
	ds_read_b128 v[98:101], v213 offset:192
	s_waitcnt lgkmcnt(0)
	v_mfma_f32_32x32x16_bf16 v[80:95], v[98:101], v[176:179], v[80:95]
	ds_read_b128 v[98:101], v213 offset:224
	s_waitcnt lgkmcnt(0)
	v_mfma_f32_32x32x16_bf16 v[80:95], v[98:101], v[180:183], v[80:95]
	ds_read_b128 v[98:101], v213 offset:256
	s_waitcnt lgkmcnt(0)
	v_mfma_f32_32x32x16_bf16 v[80:95], v[98:101], v[148:151], v[80:95]
	ds_read_b128 v[98:101], v213 offset:288
	s_waitcnt lgkmcnt(0)
	v_mfma_f32_32x32x16_bf16 v[80:95], v[98:101], v[144:147], v[80:95]
	ds_read_b128 v[98:101], v213 offset:320
	s_waitcnt lgkmcnt(0)
	v_mfma_f32_32x32x16_bf16 v[80:95], v[98:101], v[140:143], v[80:95]
	ds_read_b128 v[98:101], v213 offset:352
	s_waitcnt lgkmcnt(0)
	v_mfma_f32_32x32x16_bf16 v[80:95], v[98:101], v[136:139], v[80:95]
	ds_read_b128 v[98:101], v213 offset:12800
	s_waitcnt lgkmcnt(0)
	v_mfma_f32_32x32x16_bf16 v[64:79], v[98:101], v[152:155], v[64:79]
	ds_read_b128 v[98:101], v213 offset:12832
	s_waitcnt lgkmcnt(0)
	v_mfma_f32_32x32x16_bf16 v[64:79], v[98:101], v[156:159], v[64:79]
	ds_read_b128 v[98:101], v213 offset:12864
	s_waitcnt lgkmcnt(0)
	v_mfma_f32_32x32x16_bf16 v[64:79], v[98:101], v[160:163], v[64:79]
	ds_read_b128 v[98:101], v213 offset:12896
	s_waitcnt lgkmcnt(0)
	v_mfma_f32_32x32x16_bf16 v[64:79], v[98:101], v[164:167], v[64:79]
	ds_read_b128 v[98:101], v213 offset:12928
	s_waitcnt lgkmcnt(0)
	v_mfma_f32_32x32x16_bf16 v[64:79], v[98:101], v[168:171], v[64:79]
	ds_read_b128 v[98:101], v213 offset:12960
	s_waitcnt lgkmcnt(0)
	v_mfma_f32_32x32x16_bf16 v[64:79], v[98:101], v[172:175], v[64:79]
	ds_read_b128 v[98:101], v213 offset:12992
	s_waitcnt lgkmcnt(0)
	v_mfma_f32_32x32x16_bf16 v[64:79], v[98:101], v[176:179], v[64:79]
	ds_read_b128 v[98:101], v213 offset:13024
	s_waitcnt lgkmcnt(0)
	v_mfma_f32_32x32x16_bf16 v[64:79], v[98:101], v[180:183], v[64:79]
	ds_read_b128 v[98:101], v213 offset:13056
	s_waitcnt lgkmcnt(0)
	v_mfma_f32_32x32x16_bf16 v[64:79], v[98:101], v[148:151], v[64:79]
	ds_read_b128 v[98:101], v213 offset:13088
	s_waitcnt lgkmcnt(0)
	v_mfma_f32_32x32x16_bf16 v[64:79], v[98:101], v[144:147], v[64:79]
	ds_read_b128 v[98:101], v213 offset:13120
	s_waitcnt lgkmcnt(0)
	v_mfma_f32_32x32x16_bf16 v[64:79], v[98:101], v[140:143], v[64:79]
	ds_read_b128 v[98:101], v213 offset:13152
	s_waitcnt lgkmcnt(0)
	v_mfma_f32_32x32x16_bf16 v[64:79], v[98:101], v[136:139], v[64:79]
	v_readlane_b32 s36, v253, 22
	v_readlane_b32 s37, v253, 23
	v_readlane_b32 s38, v253, 24
	v_readlane_b32 s39, v253, 25
	s_nop 4
	s_mul_i32 s40, s17, 0x6400
	v_add_u32_e32 v230, s40, v213
	ds_read_b128 v[244:247], v230
	ds_read_b128 v[248:251], v230 offset:32
	ds_read_b128 v[232:235], v230 offset:64
.LBB0_885:
	s_add_i32 s22, s24, 2
	s_min_u32 s1, s22, s18
	s_mul_i32 s8, s16, 0x6400
	s_mov_b32 s21, s17
	s_mov_b32 s17, s0
	s_mul_i32 s0, s1, 0x30000
	s_and_b64 vcc, exec, s[4:5]
	s_add_i32 s23, s8, 0
	s_cbranch_vccnz .LBB0_887
	s_add_i32 m0, s23, 0x6000
	s_nop 4
	buffer_load_dwordx4 v207, s[36:39], s0 offen lds
.LBB0_887:
	s_lshl_b32 s25, s1, 17
	s_mul_i32 s1, s16, 0x5000
	s_add_i32 s26, s1, 0
	s_and_b64 vcc, exec, s[6:7]
	s_add_i32 s26, s26, 0x12c00
	s_cbranch_vccnz .LBB0_889
	s_add_i32 s1, s26, s2
	s_add_i32 m0, s1, 0x4000
	s_mov_b32 s14, s38
	s_mov_b32 s15, s39
	buffer_load_dwordx4 v211, s[12:15], s25 offen lds
.LBB0_889:
	s_mul_i32 s1, s21, 0x6400
	s_cmp_eq_u32 s19, s24
	s_cselect_b64 s[8:9], -1, 0
	s_add_i32 s1, s23, s10
	s_mov_b32 m0, s1
	v_xor_b32_e32 v96, 0x80000000, v199
	v_mov_b32_e32 v97, v96
	buffer_load_dwordx4 v201, s[36:39], s0 offen lds
	v_mov_b32_e32 v98, v96
	v_mov_b32_e32 v99, v96
	v_mov_b32_e32 v100, v96
	v_mov_b32_e32 v101, v96
	v_mov_b32_e32 v102, v96
	v_mov_b32_e32 v103, v96
	v_mov_b32_e32 v104, v96
	v_mov_b32_e32 v105, v96
	v_mov_b32_e32 v106, v96
	v_mov_b32_e32 v107, v96
	v_mov_b32_e32 v108, v96
	v_mov_b32_e32 v109, v96
	v_mov_b32_e32 v110, v96
	v_mov_b32_e32 v111, v96
	s_waitcnt lgkmcnt(2)
	s_nop 0
	v_mfma_f32_32x32x16_bf16 v[112:127], v[244:247], v[152:155], v[96:111]
	v_max_f32_e32 v184, v81, v81
	v_max_f32_e32 v185, v80, v80
	v_max_f32_e32 v184, v185, v184
	v_max3_f32 v184, v184, v82, v83
	v_max3_f32 v184, v184, v84, v85
	v_max3_f32 v192, v184, v86, v87
	s_add_i32 m0, s1, 0x2000
	ds_read_b128 v[184:187], v230 offset:96
	buffer_load_dwordx4 v203, s[36:39], s0 offen lds
	s_waitcnt lgkmcnt(2)
	v_mfma_f32_32x32x16_bf16 v[112:127], v[248:251], v[156:159], v[112:127]
	v_max3_f32 v188, v192, v88, v89
	v_max3_f32 v188, v188, v90, v91
	v_max3_f32 v188, v188, v92, v93
	v_max3_f32 v188, v188, v94, v95
	s_add_i32 m0, s1, 0x4000
	ds_read_b128 v[236:239], v230 offset:128
	buffer_load_dwordx4 v205, s[36:39], s0 offen lds
	s_waitcnt lgkmcnt(2)
	v_mfma_f32_32x32x16_bf16 v[112:127], v[232:235], v[160:163], v[112:127]
	v_max3_f32 v188, v188, v64, v65
	v_max3_f32 v188, v188, v66, v67
	v_max3_f32 v188, v188, v68, v69
	v_max3_f32 v192, v188, v70, v71
	s_add_i32 s26, s26, s10
	s_mov_b32 s14, s38
	s_mov_b32 s15, s39
	s_mov_b32 m0, s26
	ds_read_b128 v[188:191], v230 offset:160
	buffer_load_dwordx4 v209, s[12:15], s25 offen lds
	s_waitcnt lgkmcnt(2)
	v_mfma_f32_32x32x16_bf16 v[112:127], v[184:187], v[164:167], v[112:127]
	v_max3_f32 v184, v192, v72, v73
	v_max3_f32 v184, v184, v74, v75
	v_max3_f32 v184, v184, v76, v77
	v_max3_f32 v192, v184, v78, v79
	v_mov_b32_e32 v193, v192
	s_waitcnt lgkmcnt(1)
	v_mfma_f32_32x32x16_bf16 v[112:127], v[236:239], v[168:171], v[112:127]
	v_permlane32_swap_b32_e32 v192, v193
	v_max_f32_e32 v193, v193, v193
	v_max_f32_e32 v192, v192, v192
	v_max_f32_e32 v206, v192, v193
	ds_read_b128 v[184:187], v230 offset:192
	v_cmp_lt_f32_e32 vcc, s68, v206
	s_cmp_lg_u64 vcc, 0
	s_cselect_b64 s[0:1], -1, 0
	s_or_b64 s[0:1], s[8:9], s[0:1]
	s_and_b64 vcc, exec, s[0:1]
	s_cbranch_vccz .LBB0_891
	v_max_f32_e32 v192, v206, v206
	v_max_f32_e32 v192, 0, v192
	v_cndmask_b32_e64 v206, v192, v206, s[8:9]
	v_exp_f32_e64 v192, -v206
	v_add_f32_e32 v199, v199, v206
	v_pk_add_f32 v[80:81], v[80:81], v[206:207] op_sel_hi:[1,0] neg_lo:[0,1] neg_hi:[0,1]
	v_pk_add_f32 v[82:83], v[82:83], v[206:207] op_sel_hi:[1,0] neg_lo:[0,1] neg_hi:[0,1]
	v_cndmask_b32_e64 v208, v192, 1.0, s[8:9]
	v_pk_add_f32 v[84:85], v[84:85], v[206:207] op_sel_hi:[1,0] neg_lo:[0,1] neg_hi:[0,1]
	v_pk_add_f32 v[86:87], v[86:87], v[206:207] op_sel_hi:[1,0] neg_lo:[0,1] neg_hi:[0,1]
	v_pk_add_f32 v[88:89], v[88:89], v[206:207] op_sel_hi:[1,0] neg_lo:[0,1] neg_hi:[0,1]
	v_pk_add_f32 v[90:91], v[90:91], v[206:207] op_sel_hi:[1,0] neg_lo:[0,1] neg_hi:[0,1]
	v_pk_add_f32 v[92:93], v[92:93], v[206:207] op_sel_hi:[1,0] neg_lo:[0,1] neg_hi:[0,1]
	v_pk_add_f32 v[94:95], v[94:95], v[206:207] op_sel_hi:[1,0] neg_lo:[0,1] neg_hi:[0,1]
	v_pk_add_f32 v[64:65], v[64:65], v[206:207] op_sel_hi:[1,0] neg_lo:[0,1] neg_hi:[0,1]
	v_pk_add_f32 v[66:67], v[66:67], v[206:207] op_sel_hi:[1,0] neg_lo:[0,1] neg_hi:[0,1]
	v_pk_add_f32 v[68:69], v[68:69], v[206:207] op_sel_hi:[1,0] neg_lo:[0,1] neg_hi:[0,1]
	v_pk_add_f32 v[70:71], v[70:71], v[206:207] op_sel_hi:[1,0] neg_lo:[0,1] neg_hi:[0,1]
	v_pk_add_f32 v[72:73], v[72:73], v[206:207] op_sel_hi:[1,0] neg_lo:[0,1] neg_hi:[0,1]
	v_pk_add_f32 v[74:75], v[74:75], v[206:207] op_sel_hi:[1,0] neg_lo:[0,1] neg_hi:[0,1]
	v_pk_add_f32 v[76:77], v[76:77], v[206:207] op_sel_hi:[1,0] neg_lo:[0,1] neg_hi:[0,1]
	v_pk_add_f32 v[78:79], v[78:79], v[206:207] op_sel_hi:[1,0] neg_lo:[0,1] neg_hi:[0,1]
	v_mul_f32_e32 v214, v214, v208
	s_branch .LBB0_892

.LBB0_892:
	s_add_i32 m0, s26, 0x2000
	s_mov_b32 s14, s38
	s_mov_b32 s15, s39
	ds_read_b128 v[232:235], v230 offset:224
	buffer_load_dwordx4 v210, s[12:15], s25 offen lds
	s_waitcnt lgkmcnt(2)
	v_mfma_f32_32x32x16_bf16 v[112:127], v[188:191], v[172:175], v[112:127]
	v_exp_f32_e32 v80, v80
	v_exp_f32_e32 v81, v81
	s_nop 0
	v_add_f32_e32 v188, v81, v80
	v_add_f32_e32 v192, 0, v188
	s_waitcnt lgkmcnt(1)
	v_mfma_f32_32x32x16_bf16 v[112:127], v[184:187], v[176:179], v[112:127]
	v_exp_f32_e32 v82, v82
	v_exp_f32_e32 v184, v83
	ds_read_b128 v[188:191], v230 offset:256
	v_add_f32_e32 v83, v184, v82
	v_add_f32_e32 v83, v83, v192
	s_waitcnt lgkmcnt(1)
	v_mfma_f32_32x32x16_bf16 v[112:127], v[232:235], v[180:183], v[112:127]
	v_exp_f32_e32 v185, v84
	v_exp_f32_e32 v186, v85
	ds_read_b128 v[236:239], v230 offset:288
	v_add_f32_e32 v84, v186, v185
	v_add_f32_e32 v83, v84, v83
	s_waitcnt lgkmcnt(1)
	v_mfma_f32_32x32x16_bf16 v[112:127], v[188:191], v[148:151], v[112:127]
	v_exp_f32_e32 v187, v86
	v_exp_f32_e32 v188, v87
	ds_read_b128 v[232:235], v230 offset:320
	v_add_f32_e32 v84, v188, v187
	v_add_f32_e32 v85, v84, v83
	s_waitcnt lgkmcnt(1)
	v_mfma_f32_32x32x16_bf16 v[112:127], v[236:239], v[144:147], v[112:127]
	v_exp_f32_e32 v83, v88
	v_exp_f32_e32 v84, v89
	ds_read_b128 v[240:243], v230 offset:352
	v_add_f32_e32 v86, v84, v83
	v_add_f32_e32 v87, v86, v85
	s_waitcnt lgkmcnt(1)
	v_mfma_f32_32x32x16_bf16 v[112:127], v[232:235], v[140:143], v[112:127]
	v_exp_f32_e32 v85, v90
	v_exp_f32_e32 v86, v91
	ds_read_b128 v[236:239], v230 offset:12800
	v_add_f32_e32 v88, v86, v85
	v_add_f32_e32 v89, v88, v87
	s_waitcnt lgkmcnt(1)
	v_mfma_f32_32x32x16_bf16 v[112:127], v[240:243], v[136:139], v[112:127]
	v_exp_f32_e32 v87, v92
	v_exp_f32_e32 v88, v93
	ds_read_b128 v[232:235], v230 offset:12832
	v_add_f32_e32 v90, v88, v87
	v_add_f32_e32 v89, v90, v89
	s_waitcnt lgkmcnt(1)
	v_mfma_f32_32x32x16_bf16 v[96:111], v[236:239], v[152:155], v[96:111]
	v_exp_f32_e32 v91, v94
	v_exp_f32_e32 v92, v95
	ds_read_b128 v[240:243], v230 offset:12864
	v_add_f32_e32 v90, v92, v91
	v_add_f32_e32 v89, v90, v89
	s_waitcnt lgkmcnt(1)
	v_mfma_f32_32x32x16_bf16 v[96:111], v[232:235], v[156:159], v[96:111]
	v_exp_f32_e32 v64, v64
	v_exp_f32_e32 v65, v65
	ds_read_b128 v[236:239], v230 offset:12896
	v_add_f32_e32 v90, v65, v64
	v_add_f32_e32 v89, v90, v89
	s_waitcnt lgkmcnt(1)
	v_mfma_f32_32x32x16_bf16 v[96:111], v[240:243], v[160:163], v[96:111]
	v_exp_f32_e32 v66, v66
	v_exp_f32_e32 v67, v67
	ds_read_b128 v[232:235], v230 offset:12928
	v_add_f32_e32 v90, v67, v66
	v_add_f32_e32 v93, v90, v89
	s_waitcnt lgkmcnt(1)
	v_mfma_f32_32x32x16_bf16 v[96:111], v[236:239], v[164:167], v[96:111]
	v_exp_f32_e32 v89, v68
	v_exp_f32_e32 v90, v69
	ds_read_b128 v[240:243], v230 offset:12960
	v_add_f32_e32 v68, v90, v89
	v_add_f32_e32 v68, v68, v93
	s_waitcnt lgkmcnt(1)
	v_mfma_f32_32x32x16_bf16 v[96:111], v[232:235], v[168:171], v[96:111]
	v_exp_f32_e32 v93, v70
	v_exp_f32_e32 v94, v71
	ds_read_b128 v[236:239], v230 offset:12992
	v_add_f32_e32 v69, v94, v93
	v_add_f32_e32 v70, v69, v68
	s_waitcnt lgkmcnt(1)
	v_mfma_f32_32x32x16_bf16 v[96:111], v[240:243], v[172:175], v[96:111]
	v_exp_f32_e32 v68, v72
	v_exp_f32_e32 v69, v73
	ds_read_b128 v[232:235], v230 offset:13024
	v_add_f32_e32 v71, v69, v68
	v_add_f32_e32 v72, v71, v70
	s_waitcnt lgkmcnt(1)
	v_mfma_f32_32x32x16_bf16 v[96:111], v[236:239], v[176:179], v[96:111]
	v_exp_f32_e32 v70, v74
	v_exp_f32_e32 v71, v75
	ds_read_b128 v[240:243], v230 offset:13056
	v_add_f32_e32 v73, v71, v70
	v_add_f32_e32 v74, v73, v72
	s_waitcnt lgkmcnt(1)
	v_mfma_f32_32x32x16_bf16 v[96:111], v[232:235], v[180:183], v[96:111]
	v_exp_f32_e32 v72, v76
	v_exp_f32_e32 v73, v77
	ds_read_b128 v[236:239], v230 offset:13088
	v_add_f32_e32 v75, v73, v72
	v_add_f32_e32 v95, v75, v74
	s_waitcnt lgkmcnt(1)
	v_mfma_f32_32x32x16_bf16 v[96:111], v[240:243], v[148:151], v[96:111]
	v_exp_f32_e32 v74, v78
	v_exp_f32_e32 v75, v79
	ds_read_b128 v[76:79], v230 offset:13120
	v_add_f32_e32 v189, v75, v74
	v_add_f32_e32 v95, v189, v95
	s_waitcnt lgkmcnt(1)
	v_mfma_f32_32x32x16_bf16 v[96:111], v[236:239], v[144:147], v[96:111]
	ds_read_b128 v[230:233], v230 offset:13152
	v_add_f32_e32 v214, v214, v95
	s_waitcnt lgkmcnt(1)
	v_mfma_f32_32x32x16_bf16 v[96:111], v[76:79], v[140:143], v[96:111]
	s_waitcnt lgkmcnt(0)
	v_mfma_f32_32x32x16_bf16 v[96:111], v[230:233], v[136:139], v[96:111]
	s_and_b64 vcc, exec, s[0:1]
	s_cbranch_vccz .LBB0_894
	v_pk_mul_f32 v[62:63], v[62:63], v[208:209] op_sel_hi:[1,0]
	v_pk_mul_f32 v[60:61], v[60:61], v[208:209] op_sel_hi:[1,0]
	v_pk_mul_f32 v[58:59], v[58:59], v[208:209] op_sel_hi:[1,0]
	v_pk_mul_f32 v[56:57], v[56:57], v[208:209] op_sel_hi:[1,0]
	v_pk_mul_f32 v[54:55], v[54:55], v[208:209] op_sel_hi:[1,0]
	v_pk_mul_f32 v[52:53], v[52:53], v[208:209] op_sel_hi:[1,0]
	v_pk_mul_f32 v[50:51], v[50:51], v[208:209] op_sel_hi:[1,0]
	v_pk_mul_f32 v[48:49], v[48:49], v[208:209] op_sel_hi:[1,0]
	v_pk_mul_f32 v[46:47], v[46:47], v[208:209] op_sel_hi:[1,0]
	v_pk_mul_f32 v[44:45], v[44:45], v[208:209] op_sel_hi:[1,0]
	v_pk_mul_f32 v[42:43], v[42:43], v[208:209] op_sel_hi:[1,0]
	v_pk_mul_f32 v[40:41], v[40:41], v[208:209] op_sel_hi:[1,0]
	v_pk_mul_f32 v[38:39], v[38:39], v[208:209] op_sel_hi:[1,0]
	v_pk_mul_f32 v[36:37], v[36:37], v[208:209] op_sel_hi:[1,0]
	v_pk_mul_f32 v[34:35], v[34:35], v[208:209] op_sel_hi:[1,0]
	v_pk_mul_f32 v[32:33], v[32:33], v[208:209] op_sel_hi:[1,0]
	v_pk_mul_f32 v[30:31], v[30:31], v[208:209] op_sel_hi:[1,0]
	v_pk_mul_f32 v[28:29], v[28:29], v[208:209] op_sel_hi:[1,0]
	v_pk_mul_f32 v[26:27], v[26:27], v[208:209] op_sel_hi:[1,0]
	v_pk_mul_f32 v[24:25], v[24:25], v[208:209] op_sel_hi:[1,0]
	v_pk_mul_f32 v[22:23], v[22:23], v[208:209] op_sel_hi:[1,0]
	v_pk_mul_f32 v[20:21], v[20:21], v[208:209] op_sel_hi:[1,0]
	v_pk_mul_f32 v[18:19], v[18:19], v[208:209] op_sel_hi:[1,0]
	v_pk_mul_f32 v[16:17], v[16:17], v[208:209] op_sel_hi:[1,0]
	v_pk_mul_f32 v[14:15], v[14:15], v[208:209] op_sel_hi:[1,0]
	v_pk_mul_f32 v[12:13], v[12:13], v[208:209] op_sel_hi:[1,0]
	v_pk_mul_f32 v[10:11], v[10:11], v[208:209] op_sel_hi:[1,0]
	v_pk_mul_f32 v[8:9], v[8:9], v[208:209] op_sel_hi:[1,0]
	v_pk_mul_f32 v[6:7], v[6:7], v[208:209] op_sel_hi:[1,0]
	v_pk_mul_f32 v[4:5], v[4:5], v[208:209] op_sel_hi:[1,0]
	v_pk_mul_f32 v[2:3], v[2:3], v[208:209] op_sel_hi:[1,0]
	v_pk_mul_f32 v[0:1], v[0:1], v[208:209] op_sel_hi:[1,0]
	v_sub_f32_e32 v127, v127, v206
	v_sub_f32_e32 v126, v126, v206
	v_sub_f32_e32 v125, v125, v206
	v_sub_f32_e32 v124, v124, v206
	v_sub_f32_e32 v123, v123, v206
	v_sub_f32_e32 v122, v122, v206
	v_sub_f32_e32 v121, v121, v206
	v_sub_f32_e32 v120, v120, v206
	v_sub_f32_e32 v119, v119, v206
	v_sub_f32_e32 v118, v118, v206
	v_sub_f32_e32 v117, v117, v206
	v_sub_f32_e32 v116, v116, v206
	v_sub_f32_e32 v115, v115, v206
	v_sub_f32_e32 v114, v114, v206
	v_sub_f32_e32 v113, v113, v206
	v_sub_f32_e32 v112, v112, v206
	v_sub_f32_e32 v111, v111, v206
	v_sub_f32_e32 v110, v110, v206
	v_sub_f32_e32 v109, v109, v206
	v_sub_f32_e32 v108, v108, v206
	v_sub_f32_e32 v107, v107, v206
	v_sub_f32_e32 v106, v106, v206
	v_sub_f32_e32 v105, v105, v206
	v_sub_f32_e32 v104, v104, v206
	v_sub_f32_e32 v103, v103, v206
	v_sub_f32_e32 v102, v102, v206
	v_sub_f32_e32 v101, v101, v206
	v_sub_f32_e32 v100, v100, v206
	v_sub_f32_e32 v99, v99, v206
	v_sub_f32_e32 v98, v98, v206
	v_sub_f32_e32 v97, v97, v206
	v_sub_f32_e32 v96, v96, v206
.LBB0_894:
	s_mul_i32 s0, s17, 0x5000
	s_add_i32 s0, s0, 0
	s_add_i32 s0, s0, 0x12c00
	v_add_u32_e32 v95, s0, v216
	ds_read_b64_tr_b16 v[76:77], v95
	ds_read_b64_tr_b16 v[78:79], v95 offset:2560
	v_cvt_pk_bf16_f32 v230, v80, v81
	v_cvt_pk_bf16_f32 v231, v82, v184
	v_cvt_pk_bf16_f32 v232, v185, v186
	v_cvt_pk_bf16_f32 v233, v187, v188
	ds_read_b64_tr_b16 v[184:185], v95 offset:128
	ds_read_b64_tr_b16 v[186:187], v95 offset:2688
	ds_read_b64_tr_b16 v[188:189], v95 offset:192
	ds_read_b64_tr_b16 v[190:191], v95 offset:2752
	ds_read_b64_tr_b16 v[220:221], v95 offset:64
	ds_read_b64_tr_b16 v[222:223], v95 offset:2624
	s_waitcnt lgkmcnt(6)
	v_mfma_f32_32x32x16_bf16 v[48:63], v[76:79], v[230:233], v[48:63]
	ds_read_b64_tr_b16 v[244:245], v95 offset:5120
	ds_read_b64_tr_b16 v[246:247], v95 offset:7680
	v_cvt_pk_bf16_f32 v80, v83, v84
	v_cvt_pk_bf16_f32 v81, v85, v86
	v_cvt_pk_bf16_f32 v82, v87, v88
	v_cvt_pk_bf16_f32 v83, v91, v92
	v_cvt_pk_bf16_f32 v64, v64, v65
	v_cvt_pk_bf16_f32 v65, v66, v67
	s_waitcnt lgkmcnt(6)
	v_mfma_f32_32x32x16_bf16 v[16:31], v[184:187], v[230:233], v[16:31]
	ds_read_b64_tr_b16 v[248:249], v95 offset:5184
	ds_read_b64_tr_b16 v[250:251], v95 offset:7744
	v_cvt_pk_bf16_f32 v66, v89, v90
	v_cvt_pk_bf16_f32 v67, v93, v94
	v_cvt_pk_bf16_f32 v68, v68, v69
	v_cvt_pk_bf16_f32 v69, v70, v71
	v_cvt_pk_bf16_f32 v70, v72, v73
	v_cvt_pk_bf16_f32 v71, v74, v75
	s_waitcnt lgkmcnt(6)
	v_mfma_f32_32x32x16_bf16 v[0:15], v[188:191], v[230:233], v[0:15]
	ds_read_b64_tr_b16 v[76:77], v95 offset:5248
	ds_read_b64_tr_b16 v[78:79], v95 offset:7808
	s_add_i32 s1, s24, 3
	s_min_u32 s8, s1, s18
	s_mul_i32 s9, s17, 0x6400
	s_mul_i32 s1, s8, 0x30000
	s_add_i32 s9, s9, 0
	s_and_b64 vcc, exec, s[4:5]
	s_waitcnt lgkmcnt(6)
	v_mfma_f32_32x32x16_bf16 v[32:47], v[220:223], v[230:233], v[32:47]
	ds_read_b64_tr_b16 v[184:185], v95 offset:5312
	ds_read_b64_tr_b16 v[186:187], v95 offset:7872
	s_waitcnt lgkmcnt(6)
	v_mfma_f32_32x32x16_bf16 v[48:63], v[244:247], v[80:83], v[48:63]
	ds_read_b64_tr_b16 v[188:189], v95 offset:10240
	ds_read_b64_tr_b16 v[190:191], v95 offset:12800
	s_waitcnt lgkmcnt(6)
	v_mfma_f32_32x32x16_bf16 v[32:47], v[248:251], v[80:83], v[32:47]
	ds_read_b64_tr_b16 v[220:221], v95 offset:10304
	ds_read_b64_tr_b16 v[222:223], v95 offset:12864
	s_waitcnt lgkmcnt(6)
	v_mfma_f32_32x32x16_bf16 v[16:31], v[76:79], v[80:83], v[16:31]
	ds_read_b64_tr_b16 v[244:245], v95 offset:10368
	ds_read_b64_tr_b16 v[246:247], v95 offset:12928
	s_waitcnt lgkmcnt(6)
	v_mfma_f32_32x32x16_bf16 v[0:15], v[184:187], v[80:83], v[0:15]
	ds_read_b64_tr_b16 v[248:249], v95 offset:10432
	ds_read_b64_tr_b16 v[250:251], v95 offset:12992
	s_waitcnt lgkmcnt(6)
	v_mfma_f32_32x32x16_bf16 v[48:63], v[188:191], v[64:67], v[48:63]
	ds_read_b64_tr_b16 v[76:77], v95 offset:15360
	ds_read_b64_tr_b16 v[78:79], v95 offset:17920
	s_waitcnt lgkmcnt(6)
	v_mfma_f32_32x32x16_bf16 v[32:47], v[220:223], v[64:67], v[32:47]
	ds_read_b64_tr_b16 v[184:185], v95 offset:15424
	ds_read_b64_tr_b16 v[186:187], v95 offset:17984
	s_waitcnt lgkmcnt(6)
	v_mfma_f32_32x32x16_bf16 v[16:31], v[244:247], v[64:67], v[16:31]
	ds_read_b64_tr_b16 v[188:189], v95 offset:15488
	ds_read_b64_tr_b16 v[190:191], v95 offset:18048
	s_waitcnt lgkmcnt(6)
	v_mfma_f32_32x32x16_bf16 v[0:15], v[248:251], v[64:67], v[0:15]
	ds_read_b64_tr_b16 v[220:221], v95 offset:15552
	ds_read_b64_tr_b16 v[222:223], v95 offset:18112
	s_waitcnt lgkmcnt(6)
	v_mfma_f32_32x32x16_bf16 v[48:63], v[76:79], v[68:71], v[48:63]
	s_waitcnt lgkmcnt(4)
	v_mfma_f32_32x32x16_bf16 v[32:47], v[184:187], v[68:71], v[32:47]
	s_waitcnt vmcnt(0)
	s_waitcnt lgkmcnt(0)
	s_barrier
	v_add_u32_e32 v230, s23, v212
	ds_read_b128 v[244:247], v230
	ds_read_b128 v[248:251], v230 offset:32
	ds_read_b128 v[232:235], v230 offset:64
	v_mfma_f32_32x32x16_bf16 v[16:31], v[188:191], v[68:71], v[16:31]
	v_mfma_f32_32x32x16_bf16 v[0:15], v[220:223], v[68:71], v[0:15]
	s_cbranch_vccz .LBB0_899
	s_and_b64 vcc, exec, s[6:7]
	s_lshl_b32 s8, s8, 17
	s_cbranch_vccnz .LBB0_897
.LBB0_896:
	s_add_i32 s14, s0, s2
	s_add_i32 m0, s14, 0x4000
	s_mov_b32 s14, s38
	s_mov_b32 s15, s39
	buffer_load_dwordx4 v211, s[12:15], s8 offen lds
.LBB0_897:
	s_add_i32 s9, s9, s10
	s_mov_b32 m0, s9
	v_xor_b32_e32 v64, 0x80000000, v199
	v_mov_b32_e32 v65, v64
	buffer_load_dwordx4 v201, s[36:39], s1 offen lds
	v_mov_b32_e32 v66, v64
	v_mov_b32_e32 v67, v64
	v_mov_b32_e32 v68, v64
	v_mov_b32_e32 v69, v64
	v_mov_b32_e32 v70, v64
	v_mov_b32_e32 v71, v64
	v_mov_b32_e32 v72, v64
	v_mov_b32_e32 v73, v64
	v_mov_b32_e32 v74, v64
	v_mov_b32_e32 v75, v64
	v_mov_b32_e32 v76, v64
	v_mov_b32_e32 v77, v64
	v_mov_b32_e32 v78, v64
	v_mov_b32_e32 v79, v64
	s_waitcnt lgkmcnt(2)
	s_nop 0
	v_mfma_f32_32x32x16_bf16 v[80:95], v[244:247], v[152:155], v[64:79]
	v_max_f32_e32 v184, v113, v113
	v_max_f32_e32 v185, v112, v112
	v_max_f32_e32 v184, v185, v184
	v_max3_f32 v184, v184, v114, v115
	v_max3_f32 v184, v184, v116, v117
	v_max3_f32 v192, v184, v118, v119
	s_add_i32 m0, s9, 0x2000
	ds_read_b128 v[184:187], v230 offset:96
	buffer_load_dwordx4 v203, s[36:39], s1 offen lds
	s_waitcnt lgkmcnt(2)
	v_mfma_f32_32x32x16_bf16 v[80:95], v[248:251], v[156:159], v[80:95]
	v_max3_f32 v188, v192, v120, v121
	v_max3_f32 v188, v188, v122, v123
	v_max3_f32 v188, v188, v124, v125
	v_max3_f32 v188, v188, v126, v127
	s_add_i32 m0, s9, 0x4000
	ds_read_b128 v[236:239], v230 offset:128
	buffer_load_dwordx4 v205, s[36:39], s1 offen lds
	s_waitcnt lgkmcnt(2)
	v_mfma_f32_32x32x16_bf16 v[80:95], v[232:235], v[160:163], v[80:95]
	v_max3_f32 v188, v188, v96, v97
	v_max3_f32 v188, v188, v98, v99
	v_max3_f32 v188, v188, v100, v101
	v_max3_f32 v192, v188, v102, v103
	s_add_i32 s9, s0, s10
	s_mov_b32 s14, s38
	s_mov_b32 s15, s39
	s_mov_b32 m0, s9
	ds_read_b128 v[188:191], v230 offset:160
	buffer_load_dwordx4 v209, s[12:15], s8 offen lds
	s_waitcnt lgkmcnt(2)
	v_mfma_f32_32x32x16_bf16 v[80:95], v[184:187], v[164:167], v[80:95]
	v_max3_f32 v184, v192, v104, v105
	v_max3_f32 v184, v184, v106, v107
	v_max3_f32 v184, v184, v108, v109
	v_max3_f32 v192, v184, v110, v111
	s_waitcnt lgkmcnt(1)
	v_mfma_f32_32x32x16_bf16 v[80:95], v[236:239], v[168:171], v[80:95]
	v_mov_b32_e32 v193, v192
	s_nop 1
	v_permlane32_swap_b32_e32 v192, v193
	ds_read_b128 v[184:187], v230 offset:192
	v_max_f32_e32 v193, v193, v193
	v_max_f32_e32 v192, v192, v192
	v_max_f32_e32 v206, v192, v193
	v_cmp_lt_f32_e32 vcc, s68, v206
	s_cmp_lg_u64 vcc, 0
	s_cselect_b64 s[0:1], -1, 0
	s_cbranch_vccz .LBB0_900
	v_max_f32_e32 v192, v206, v206
	v_max_f32_e32 v206, 0, v192
	v_exp_f32_e64 v208, -v206
	v_add_f32_e32 v199, v199, v206
	v_pk_add_f32 v[112:113], v[112:113], v[206:207] op_sel_hi:[1,0] neg_lo:[0,1] neg_hi:[0,1]
	v_pk_add_f32 v[114:115], v[114:115], v[206:207] op_sel_hi:[1,0] neg_lo:[0,1] neg_hi:[0,1]
	v_pk_add_f32 v[116:117], v[116:117], v[206:207] op_sel_hi:[1,0] neg_lo:[0,1] neg_hi:[0,1]
	v_pk_add_f32 v[118:119], v[118:119], v[206:207] op_sel_hi:[1,0] neg_lo:[0,1] neg_hi:[0,1]
	v_pk_add_f32 v[120:121], v[120:121], v[206:207] op_sel_hi:[1,0] neg_lo:[0,1] neg_hi:[0,1]
	v_pk_add_f32 v[122:123], v[122:123], v[206:207] op_sel_hi:[1,0] neg_lo:[0,1] neg_hi:[0,1]
	v_pk_add_f32 v[124:125], v[124:125], v[206:207] op_sel_hi:[1,0] neg_lo:[0,1] neg_hi:[0,1]
	v_pk_add_f32 v[126:127], v[126:127], v[206:207] op_sel_hi:[1,0] neg_lo:[0,1] neg_hi:[0,1]
	v_pk_add_f32 v[96:97], v[96:97], v[206:207] op_sel_hi:[1,0] neg_lo:[0,1] neg_hi:[0,1]
	v_pk_add_f32 v[98:99], v[98:99], v[206:207] op_sel_hi:[1,0] neg_lo:[0,1] neg_hi:[0,1]
	v_pk_add_f32 v[100:101], v[100:101], v[206:207] op_sel_hi:[1,0] neg_lo:[0,1] neg_hi:[0,1]
	v_pk_add_f32 v[102:103], v[102:103], v[206:207] op_sel_hi:[1,0] neg_lo:[0,1] neg_hi:[0,1]
	v_pk_add_f32 v[104:105], v[104:105], v[206:207] op_sel_hi:[1,0] neg_lo:[0,1] neg_hi:[0,1]
	v_pk_add_f32 v[106:107], v[106:107], v[206:207] op_sel_hi:[1,0] neg_lo:[0,1] neg_hi:[0,1]
	v_pk_add_f32 v[108:109], v[108:109], v[206:207] op_sel_hi:[1,0] neg_lo:[0,1] neg_hi:[0,1]
	v_pk_add_f32 v[110:111], v[110:111], v[206:207] op_sel_hi:[1,0] neg_lo:[0,1] neg_hi:[0,1]
	v_mul_f32_e32 v214, v214, v208
	s_branch .LBB0_901
.LBB0_899:
	s_add_i32 m0, s9, 0x6000
	s_nop 4
	buffer_load_dwordx4 v207, s[36:39], s1 offen lds
	s_and_b64 vcc, exec, s[6:7]
	s_lshl_b32 s8, s8, 17
	s_cbranch_vccz .LBB0_896
	s_branch .LBB0_897

.LBB0_901:
	s_add_i32 m0, s9, 0x2000
	s_mov_b32 s14, s38
	s_mov_b32 s15, s39
	ds_read_b128 v[232:235], v230 offset:224
	buffer_load_dwordx4 v210, s[12:15], s8 offen lds
	s_waitcnt lgkmcnt(2)
	v_mfma_f32_32x32x16_bf16 v[80:95], v[188:191], v[172:175], v[80:95]
	v_exp_f32_e32 v112, v112
	v_exp_f32_e32 v113, v113
	s_nop 0
	v_add_f32_e32 v188, v113, v112
	v_add_f32_e32 v192, 0, v188
	s_waitcnt lgkmcnt(1)
	v_mfma_f32_32x32x16_bf16 v[80:95], v[184:187], v[176:179], v[80:95]
	v_exp_f32_e32 v114, v114
	v_exp_f32_e32 v184, v115
	ds_read_b128 v[188:191], v230 offset:256
	v_add_f32_e32 v115, v184, v114
	v_add_f32_e32 v115, v115, v192
	s_waitcnt lgkmcnt(1)
	v_mfma_f32_32x32x16_bf16 v[80:95], v[232:235], v[180:183], v[80:95]
	v_exp_f32_e32 v185, v116
	v_exp_f32_e32 v186, v117
	ds_read_b128 v[236:239], v230 offset:288
	v_add_f32_e32 v116, v186, v185
	v_add_f32_e32 v115, v116, v115
	s_waitcnt lgkmcnt(1)
	v_mfma_f32_32x32x16_bf16 v[80:95], v[188:191], v[148:151], v[80:95]
	v_exp_f32_e32 v187, v118
	v_exp_f32_e32 v188, v119
	ds_read_b128 v[232:235], v230 offset:320
	v_add_f32_e32 v116, v188, v187
	v_add_f32_e32 v117, v116, v115
	s_waitcnt lgkmcnt(1)
	v_mfma_f32_32x32x16_bf16 v[80:95], v[236:239], v[144:147], v[80:95]
	v_exp_f32_e32 v115, v120
	v_exp_f32_e32 v116, v121
	ds_read_b128 v[240:243], v230 offset:352
	v_add_f32_e32 v118, v116, v115
	v_add_f32_e32 v119, v118, v117
	s_waitcnt lgkmcnt(1)
	v_mfma_f32_32x32x16_bf16 v[80:95], v[232:235], v[140:143], v[80:95]
	v_exp_f32_e32 v117, v122
	v_exp_f32_e32 v118, v123
	ds_read_b128 v[236:239], v230 offset:12800
	v_add_f32_e32 v120, v118, v117
	v_add_f32_e32 v121, v120, v119
	s_waitcnt lgkmcnt(1)
	v_mfma_f32_32x32x16_bf16 v[80:95], v[240:243], v[136:139], v[80:95]
	v_exp_f32_e32 v119, v124
	v_exp_f32_e32 v120, v125
	ds_read_b128 v[232:235], v230 offset:12832
	v_add_f32_e32 v122, v120, v119
	v_add_f32_e32 v121, v122, v121
	s_waitcnt lgkmcnt(1)
	v_mfma_f32_32x32x16_bf16 v[64:79], v[236:239], v[152:155], v[64:79]
	v_exp_f32_e32 v123, v126
	v_exp_f32_e32 v124, v127
	ds_read_b128 v[240:243], v230 offset:12864
	v_add_f32_e32 v122, v124, v123
	v_add_f32_e32 v121, v122, v121
	s_waitcnt lgkmcnt(1)
	v_mfma_f32_32x32x16_bf16 v[64:79], v[232:235], v[156:159], v[64:79]
	v_exp_f32_e32 v96, v96
	v_exp_f32_e32 v97, v97
	ds_read_b128 v[236:239], v230 offset:12896
	v_add_f32_e32 v122, v97, v96
	v_add_f32_e32 v121, v122, v121
	s_waitcnt lgkmcnt(1)
	v_mfma_f32_32x32x16_bf16 v[64:79], v[240:243], v[160:163], v[64:79]
	v_exp_f32_e32 v98, v98
	v_exp_f32_e32 v99, v99
	ds_read_b128 v[232:235], v230 offset:12928
	v_add_f32_e32 v122, v99, v98
	v_add_f32_e32 v125, v122, v121
	s_waitcnt lgkmcnt(1)
	v_mfma_f32_32x32x16_bf16 v[64:79], v[236:239], v[164:167], v[64:79]
	v_exp_f32_e32 v121, v100
	v_exp_f32_e32 v122, v101
	ds_read_b128 v[240:243], v230 offset:12960
	v_add_f32_e32 v100, v122, v121
	v_add_f32_e32 v100, v100, v125
	s_waitcnt lgkmcnt(1)
	v_mfma_f32_32x32x16_bf16 v[64:79], v[232:235], v[168:171], v[64:79]
	v_exp_f32_e32 v125, v102
	v_exp_f32_e32 v126, v103
	ds_read_b128 v[236:239], v230 offset:12992
	v_add_f32_e32 v101, v126, v125
	v_add_f32_e32 v102, v101, v100
	s_waitcnt lgkmcnt(1)
	v_mfma_f32_32x32x16_bf16 v[64:79], v[240:243], v[172:175], v[64:79]
	v_exp_f32_e32 v100, v104
	v_exp_f32_e32 v101, v105
	ds_read_b128 v[232:235], v230 offset:13024
	v_add_f32_e32 v103, v101, v100
	v_add_f32_e32 v104, v103, v102
	s_waitcnt lgkmcnt(1)
	v_mfma_f32_32x32x16_bf16 v[64:79], v[236:239], v[176:179], v[64:79]
	v_exp_f32_e32 v102, v106
	v_exp_f32_e32 v103, v107
	ds_read_b128 v[240:243], v230 offset:13056
	v_add_f32_e32 v105, v103, v102
	v_add_f32_e32 v106, v105, v104
	s_waitcnt lgkmcnt(1)
	v_mfma_f32_32x32x16_bf16 v[64:79], v[232:235], v[180:183], v[64:79]
	v_exp_f32_e32 v104, v108
	v_exp_f32_e32 v105, v109
	ds_read_b128 v[236:239], v230 offset:13088
	v_add_f32_e32 v107, v105, v104
	v_add_f32_e32 v127, v107, v106
	s_waitcnt lgkmcnt(1)
	v_mfma_f32_32x32x16_bf16 v[64:79], v[240:243], v[148:151], v[64:79]
	v_exp_f32_e32 v106, v110
	v_exp_f32_e32 v107, v111
	ds_read_b128 v[108:111], v230 offset:13120
	v_add_f32_e32 v189, v107, v106
	v_add_f32_e32 v127, v189, v127
	s_waitcnt lgkmcnt(1)
	v_mfma_f32_32x32x16_bf16 v[64:79], v[236:239], v[144:147], v[64:79]
	ds_read_b128 v[230:233], v230 offset:13152
	v_add_f32_e32 v214, v214, v127
	s_waitcnt lgkmcnt(1)
	v_mfma_f32_32x32x16_bf16 v[64:79], v[108:111], v[140:143], v[64:79]
	s_waitcnt lgkmcnt(0)
	v_mfma_f32_32x32x16_bf16 v[64:79], v[230:233], v[136:139], v[64:79]
	s_and_b64 vcc, exec, s[0:1]
	s_cbranch_vccz .LBB0_903
; __device__ __forceinline__ void mla_unit(const Frame& F, int h, int q0, int key0, int ntiles, int mode, int su) {
;     ...
;     for (int t = 0; t < ntiles; t += 2) { MLA_STEP(sA, sB, t); MLA_STEP(sB, sA, t + 1); }
	v_pk_mul_f32 v[62:63], v[62:63], v[208:209] op_sel_hi:[1,0]
	v_pk_mul_f32 v[60:61], v[60:61], v[208:209] op_sel_hi:[1,0]
	v_pk_mul_f32 v[58:59], v[58:59], v[208:209] op_sel_hi:[1,0]
	v_pk_mul_f32 v[56:57], v[56:57], v[208:209] op_sel_hi:[1,0]
	v_pk_mul_f32 v[54:55], v[54:55], v[208:209] op_sel_hi:[1,0]
	v_pk_mul_f32 v[52:53], v[52:53], v[208:209] op_sel_hi:[1,0]
	v_pk_mul_f32 v[50:51], v[50:51], v[208:209] op_sel_hi:[1,0]
	v_pk_mul_f32 v[48:49], v[48:49], v[208:209] op_sel_hi:[1,0]
	v_pk_mul_f32 v[46:47], v[46:47], v[208:209] op_sel_hi:[1,0]
	v_pk_mul_f32 v[44:45], v[44:45], v[208:209] op_sel_hi:[1,0]
	v_pk_mul_f32 v[42:43], v[42:43], v[208:209] op_sel_hi:[1,0]
	v_pk_mul_f32 v[40:41], v[40:41], v[208:209] op_sel_hi:[1,0]
	v_pk_mul_f32 v[38:39], v[38:39], v[208:209] op_sel_hi:[1,0]
	v_pk_mul_f32 v[36:37], v[36:37], v[208:209] op_sel_hi:[1,0]
	v_pk_mul_f32 v[34:35], v[34:35], v[208:209] op_sel_hi:[1,0]
	v_pk_mul_f32 v[32:33], v[32:33], v[208:209] op_sel_hi:[1,0]
	v_pk_mul_f32 v[30:31], v[30:31], v[208:209] op_sel_hi:[1,0]
	v_pk_mul_f32 v[28:29], v[28:29], v[208:209] op_sel_hi:[1,0]
	v_pk_mul_f32 v[26:27], v[26:27], v[208:209] op_sel_hi:[1,0]
	v_pk_mul_f32 v[24:25], v[24:25], v[208:209] op_sel_hi:[1,0]
	v_pk_mul_f32 v[22:23], v[22:23], v[208:209] op_sel_hi:[1,0]
	v_pk_mul_f32 v[20:21], v[20:21], v[208:209] op_sel_hi:[1,0]
	v_pk_mul_f32 v[18:19], v[18:19], v[208:209] op_sel_hi:[1,0]
	v_pk_mul_f32 v[16:17], v[16:17], v[208:209] op_sel_hi:[1,0]
	v_pk_mul_f32 v[14:15], v[14:15], v[208:209] op_sel_hi:[1,0]
	v_pk_mul_f32 v[12:13], v[12:13], v[208:209] op_sel_hi:[1,0]
	v_pk_mul_f32 v[10:11], v[10:11], v[208:209] op_sel_hi:[1,0]
	v_pk_mul_f32 v[8:9], v[8:9], v[208:209] op_sel_hi:[1,0]
	v_pk_mul_f32 v[6:7], v[6:7], v[208:209] op_sel_hi:[1,0]
	v_pk_mul_f32 v[4:5], v[4:5], v[208:209] op_sel_hi:[1,0]
	v_pk_mul_f32 v[2:3], v[2:3], v[208:209] op_sel_hi:[1,0]
	v_pk_mul_f32 v[0:1], v[0:1], v[208:209] op_sel_hi:[1,0]
	v_sub_f32_e32 v95, v95, v206
	v_sub_f32_e32 v94, v94, v206
	v_sub_f32_e32 v93, v93, v206
	v_sub_f32_e32 v92, v92, v206
	v_sub_f32_e32 v91, v91, v206
	v_sub_f32_e32 v90, v90, v206
	v_sub_f32_e32 v89, v89, v206
	v_sub_f32_e32 v88, v88, v206
	v_sub_f32_e32 v87, v87, v206
	v_sub_f32_e32 v86, v86, v206
	v_sub_f32_e32 v85, v85, v206
	v_sub_f32_e32 v84, v84, v206
	v_sub_f32_e32 v83, v83, v206
	v_sub_f32_e32 v82, v82, v206
	v_sub_f32_e32 v81, v81, v206
	v_sub_f32_e32 v80, v80, v206
	v_sub_f32_e32 v79, v79, v206
	v_sub_f32_e32 v78, v78, v206
	v_sub_f32_e32 v77, v77, v206
	v_sub_f32_e32 v76, v76, v206
	v_sub_f32_e32 v75, v75, v206
	v_sub_f32_e32 v74, v74, v206
	v_sub_f32_e32 v73, v73, v206
	v_sub_f32_e32 v72, v72, v206
	v_sub_f32_e32 v71, v71, v206
	v_sub_f32_e32 v70, v70, v206
	v_sub_f32_e32 v69, v69, v206
	v_sub_f32_e32 v68, v68, v206
	v_sub_f32_e32 v67, v67, v206
	v_sub_f32_e32 v66, v66, v206
	v_sub_f32_e32 v65, v65, v206
	v_sub_f32_e32 v64, v64, v206
.LBB0_903:
	s_mul_i32 s0, s21, 0x5000
	v_add_u32_e32 v127, s0, v229
	ds_read_b64_tr_b16 v[108:109], v127
	ds_read_b64_tr_b16 v[110:111], v127 offset:2560
	v_cvt_pk_bf16_f32 v230, v112, v113
	v_cvt_pk_bf16_f32 v231, v114, v184
	v_cvt_pk_bf16_f32 v232, v185, v186
	v_cvt_pk_bf16_f32 v233, v187, v188
	ds_read_b64_tr_b16 v[184:185], v127 offset:128
	ds_read_b64_tr_b16 v[186:187], v127 offset:2688
	ds_read_b64_tr_b16 v[188:189], v127 offset:192
	ds_read_b64_tr_b16 v[190:191], v127 offset:2752
	ds_read_b64_tr_b16 v[220:221], v127 offset:64
	ds_read_b64_tr_b16 v[222:223], v127 offset:2624
	s_waitcnt lgkmcnt(6)
	v_mfma_f32_32x32x16_bf16 v[48:63], v[108:111], v[230:233], v[48:63]
	ds_read_b64_tr_b16 v[244:245], v127 offset:5120
	ds_read_b64_tr_b16 v[246:247], v127 offset:7680
	v_cvt_pk_bf16_f32 v112, v115, v116
	v_cvt_pk_bf16_f32 v113, v117, v118
	v_cvt_pk_bf16_f32 v114, v119, v120
	v_cvt_pk_bf16_f32 v115, v123, v124
	v_cvt_pk_bf16_f32 v96, v96, v97
	v_cvt_pk_bf16_f32 v97, v98, v99
	s_waitcnt lgkmcnt(6)
	v_mfma_f32_32x32x16_bf16 v[16:31], v[184:187], v[230:233], v[16:31]
	ds_read_b64_tr_b16 v[248:249], v127 offset:5184
	ds_read_b64_tr_b16 v[250:251], v127 offset:7744
	v_cvt_pk_bf16_f32 v98, v121, v122
	v_cvt_pk_bf16_f32 v99, v125, v126
	v_cvt_pk_bf16_f32 v100, v100, v101
	v_cvt_pk_bf16_f32 v101, v102, v103
	v_cvt_pk_bf16_f32 v102, v104, v105
	v_cvt_pk_bf16_f32 v103, v106, v107
	s_waitcnt lgkmcnt(6)
	v_mfma_f32_32x32x16_bf16 v[0:15], v[188:191], v[230:233], v[0:15]
	ds_read_b64_tr_b16 v[108:109], v127 offset:5248
	ds_read_b64_tr_b16 v[110:111], v127 offset:7808
	s_cmp_lt_u32 s22, s3
	s_waitcnt lgkmcnt(6)
	v_mfma_f32_32x32x16_bf16 v[32:47], v[220:223], v[230:233], v[32:47]
	ds_read_b64_tr_b16 v[184:185], v127 offset:5312
	ds_read_b64_tr_b16 v[186:187], v127 offset:7872
	s_waitcnt lgkmcnt(6)
	v_mfma_f32_32x32x16_bf16 v[48:63], v[244:247], v[112:115], v[48:63]
	ds_read_b64_tr_b16 v[188:189], v127 offset:10240
	ds_read_b64_tr_b16 v[190:191], v127 offset:12800
	s_waitcnt lgkmcnt(6)
	v_mfma_f32_32x32x16_bf16 v[32:47], v[248:251], v[112:115], v[32:47]
	ds_read_b64_tr_b16 v[220:221], v127 offset:10304
	ds_read_b64_tr_b16 v[222:223], v127 offset:12864
	s_waitcnt lgkmcnt(6)
	v_mfma_f32_32x32x16_bf16 v[16:31], v[108:111], v[112:115], v[16:31]
	ds_read_b64_tr_b16 v[244:245], v127 offset:10368
	ds_read_b64_tr_b16 v[246:247], v127 offset:12928
	s_waitcnt lgkmcnt(6)
	v_mfma_f32_32x32x16_bf16 v[0:15], v[184:187], v[112:115], v[0:15]
	ds_read_b64_tr_b16 v[248:249], v127 offset:10432
	ds_read_b64_tr_b16 v[250:251], v127 offset:12992
	s_waitcnt lgkmcnt(6)
	v_mfma_f32_32x32x16_bf16 v[48:63], v[188:191], v[96:99], v[48:63]
	ds_read_b64_tr_b16 v[108:109], v127 offset:15360
	ds_read_b64_tr_b16 v[110:111], v127 offset:17920
	s_waitcnt lgkmcnt(6)
	v_mfma_f32_32x32x16_bf16 v[32:47], v[220:223], v[96:99], v[32:47]
	ds_read_b64_tr_b16 v[184:185], v127 offset:15424
	ds_read_b64_tr_b16 v[186:187], v127 offset:17984
	s_waitcnt lgkmcnt(6)
	v_mfma_f32_32x32x16_bf16 v[16:31], v[244:247], v[96:99], v[16:31]
	ds_read_b64_tr_b16 v[188:189], v127 offset:15488
	ds_read_b64_tr_b16 v[190:191], v127 offset:18048
	s_waitcnt lgkmcnt(6)
	v_mfma_f32_32x32x16_bf16 v[0:15], v[248:251], v[96:99], v[0:15]
	ds_read_b64_tr_b16 v[220:221], v127 offset:15552
	ds_read_b64_tr_b16 v[222:223], v127 offset:18112
	s_waitcnt lgkmcnt(6)
	v_mfma_f32_32x32x16_bf16 v[48:63], v[108:111], v[100:103], v[48:63]
	s_waitcnt lgkmcnt(4)
	v_mfma_f32_32x32x16_bf16 v[32:47], v[184:187], v[100:103], v[32:47]
	s_waitcnt vmcnt(0)
	s_waitcnt lgkmcnt(0)
	s_barrier
	s_mul_i32 s40, s17, 0x6400
	v_add_u32_e32 v230, s40, v213
	ds_read_b128 v[244:247], v230
	ds_read_b128 v[248:251], v230 offset:32
	ds_read_b128 v[232:235], v230 offset:64
	v_mfma_f32_32x32x16_bf16 v[16:31], v[188:191], v[100:103], v[16:31]
	v_mfma_f32_32x32x16_bf16 v[0:15], v[220:223], v[100:103], v[0:15]
	s_cbranch_scc0 .LBB0_905
	s_mov_b32 s0, s16
	s_mov_b32 s16, s21
	s_mov_b32 s24, s22
	s_branch .LBB0_885
; __device__ __forceinline__ unsigned cvt_pk_bf16(float lo, float hi) { return __builtin_bit_cast(unsigned, __builtin_convertvector((f32x2){lo, hi}, bf16x2n)); }
; __device__ __forceinline__ void mla_unit(const Frame& F, int h, int q0, int key0, int ntiles, int mode, int su) {
;     ...
;     } else {
;         float lt = l;
;         { const auto q2 = __builtin_amdgcn_permlane32_swap(__float_as_uint(lt), __float_as_uint(lt), false, false); lt = __uint_as_float(q2[0]) + __uint_as_float(q2[1]); }
;         const float inv = 1.0f / lt;
;         bf16_t* op = YC + (size_t)qr * 3072 + 1024 + h * VDIM + 4 * hh;
; #pragma unroll
;         for (int dt = 0; dt < 4; ++dt)
; #pragma unroll
;             for (int rg = 0; rg < 4; ++rg) { u32x2 w; w.x = cvt_pk_bf16(O[dt][4 * rg] * inv, O[dt][4 * rg + 1] * inv); w.y = cvt_pk_bf16(O[dt][4 * rg + 2] * inv, O[dt][4 * rg + 3] * inv);
;                 *(u32x2*)(op + 32 * dt + 8 * rg) = w; }
;     }
.LBB0_905:
	s_waitcnt lgkmcnt(0)
	v_mov_b32_e32 v64, v214
	s_nop 1
	v_permlane32_swap_b32_e32 v214, v64
	v_add_f32_e32 v64, v214, v64
	v_div_scale_f32 v65, s[0:1], v64, v64, 1.0
	v_rcp_f32_e32 v66, v65
	s_movk_i32 s0, 0x1800
	s_lshl_b32 s72, s11, 1
	v_ashrrev_i32_e32 v205, 31, v204
	v_fma_f32 v67, -v65, v66, 1.0
	v_fmac_f32_e32 v66, v67, v66
	v_div_scale_f32 v67, vcc, 1.0, v64, 1.0
	v_mul_f32_e32 v68, v67, v66
	v_fma_f32 v69, -v65, v68, v67
	v_fmac_f32_e32 v68, v69, v66
	v_fma_f32 v65, -v65, v68, v67
	v_div_fmas_f32 v65, v65, v66, v68
	v_mov_b64_e32 v[66:67], s[80:81]
	v_mad_i64_i32 v[66:67], s[0:1], v200, s0, v[66:67]
	v_lshl_add_u64 v[66:67], v[66:67], 0, s[72:73]
	v_div_fixup_f32 v64, v65, v64, 1.0
	v_lshl_add_u64 v[66:67], v[204:205], 1, v[66:67]
	s_mov_b64 s[0:1], 0x52524800
	v_lshl_add_u64 v[68:69], v[66:67], 0, s[0:1]
	v_pk_mul_f32 v[48:49], v[48:49], v[64:65] op_sel_hi:[1,0]
	v_pk_mul_f32 v[50:51], v[50:51], v[64:65] op_sel_hi:[1,0]
	s_mov_b32 s0, 0x52524000
	v_cvt_pk_bf16_f32 v48, v48, v49
	v_cvt_pk_bf16_f32 v49, v50, v51
	v_add_co_u32_e32 v50, vcc, s0, v66
	v_pk_mul_f32 v[32:33], v[32:33], v[64:65] op_sel_hi:[1,0]
	v_pk_mul_f32 v[34:35], v[34:35], v[64:65] op_sel_hi:[1,0]
	v_pk_mul_f32 v[16:17], v[16:17], v[64:65] op_sel_hi:[1,0]
	v_pk_mul_f32 v[18:19], v[18:19], v[64:65] op_sel_hi:[1,0]
	v_pk_mul_f32 v[0:1], v[0:1], v[64:65] op_sel_hi:[1,0]
	v_pk_mul_f32 v[2:3], v[2:3], v[64:65] op_sel_hi:[1,0]
	v_addc_co_u32_e32 v51, vcc, 0, v67, vcc
	v_cvt_pk_bf16_f32 v32, v32, v33
	v_cvt_pk_bf16_f32 v33, v34, v35
	v_cvt_pk_bf16_f32 v16, v16, v17
	v_cvt_pk_bf16_f32 v17, v18, v19
	v_cvt_pk_bf16_f32 v0, v0, v1
	v_cvt_pk_bf16_f32 v1, v2, v3
	flat_store_dwordx2 v[50:51], v[48:49] offset:2048
	v_pk_mul_f32 v[48:49], v[52:53], v[64:65] op_sel_hi:[1,0]
	v_pk_mul_f32 v[50:51], v[54:55], v[64:65] op_sel_hi:[1,0]
	flat_store_dwordx2 v[68:69], v[32:33] offset:64
	v_pk_mul_f32 v[32:33], v[36:37], v[64:65] op_sel_hi:[1,0]
	v_pk_mul_f32 v[34:35], v[38:39], v[64:65] op_sel_hi:[1,0]
	flat_store_dwordx2 v[68:69], v[16:17] offset:128
	v_pk_mul_f32 v[16:17], v[20:21], v[64:65] op_sel_hi:[1,0]
	v_pk_mul_f32 v[18:19], v[22:23], v[64:65] op_sel_hi:[1,0]
	flat_store_dwordx2 v[68:69], v[0:1] offset:192
	v_pk_mul_f32 v[0:1], v[4:5], v[64:65] op_sel_hi:[1,0]
	v_pk_mul_f32 v[2:3], v[6:7], v[64:65] op_sel_hi:[1,0]
	v_cvt_pk_bf16_f32 v48, v48, v49
	v_cvt_pk_bf16_f32 v49, v50, v51
	v_cvt_pk_bf16_f32 v32, v32, v33
	v_cvt_pk_bf16_f32 v33, v34, v35
	v_cvt_pk_bf16_f32 v16, v16, v17
	v_cvt_pk_bf16_f32 v17, v18, v19
	v_cvt_pk_bf16_f32 v0, v0, v1
	v_cvt_pk_bf16_f32 v1, v2, v3
	flat_store_dwordx2 v[68:69], v[48:49] offset:16
	v_pk_mul_f32 v[48:49], v[56:57], v[64:65] op_sel_hi:[1,0]
	v_pk_mul_f32 v[50:51], v[58:59], v[64:65] op_sel_hi:[1,0]
	flat_store_dwordx2 v[68:69], v[32:33] offset:80
	v_pk_mul_f32 v[32:33], v[40:41], v[64:65] op_sel_hi:[1,0]
	v_pk_mul_f32 v[34:35], v[42:43], v[64:65] op_sel_hi:[1,0]
	flat_store_dwordx2 v[68:69], v[16:17] offset:144
	v_pk_mul_f32 v[16:17], v[24:25], v[64:65] op_sel_hi:[1,0]
	v_pk_mul_f32 v[18:19], v[26:27], v[64:65] op_sel_hi:[1,0]
	flat_store_dwordx2 v[68:69], v[0:1] offset:208
	v_pk_mul_f32 v[0:1], v[8:9], v[64:65] op_sel_hi:[1,0]
	v_pk_mul_f32 v[2:3], v[10:11], v[64:65] op_sel_hi:[1,0]
	v_cvt_pk_bf16_f32 v48, v48, v49
	v_cvt_pk_bf16_f32 v49, v50, v51
	v_cvt_pk_bf16_f32 v32, v32, v33
	v_cvt_pk_bf16_f32 v33, v34, v35
	v_cvt_pk_bf16_f32 v16, v16, v17
	v_cvt_pk_bf16_f32 v17, v18, v19
	v_cvt_pk_bf16_f32 v0, v0, v1
	v_cvt_pk_bf16_f32 v1, v2, v3
	flat_store_dwordx2 v[68:69], v[48:49] offset:32
	v_pk_mul_f32 v[48:49], v[60:61], v[64:65] op_sel_hi:[1,0]
	v_pk_mul_f32 v[50:51], v[62:63], v[64:65] op_sel_hi:[1,0]
	flat_store_dwordx2 v[68:69], v[32:33] offset:96
	v_pk_mul_f32 v[32:33], v[44:45], v[64:65] op_sel_hi:[1,0]
	v_pk_mul_f32 v[34:35], v[46:47], v[64:65] op_sel_hi:[1,0]
	flat_store_dwordx2 v[68:69], v[16:17] offset:160
	v_pk_mul_f32 v[16:17], v[28:29], v[64:65] op_sel_hi:[1,0]
	v_pk_mul_f32 v[18:19], v[30:31], v[64:65] op_sel_hi:[1,0]
	flat_store_dwordx2 v[68:69], v[0:1] offset:224
	v_pk_mul_f32 v[0:1], v[12:13], v[64:65] op_sel_hi:[1,0]
	v_pk_mul_f32 v[2:3], v[14:15], v[64:65] op_sel_hi:[1,0]
	v_cvt_pk_bf16_f32 v48, v48, v49
	v_cvt_pk_bf16_f32 v49, v50, v51
	v_cvt_pk_bf16_f32 v32, v32, v33
	v_cvt_pk_bf16_f32 v33, v34, v35
	v_cvt_pk_bf16_f32 v16, v16, v17
	v_cvt_pk_bf16_f32 v17, v18, v19
	v_cvt_pk_bf16_f32 v0, v0, v1
	v_cvt_pk_bf16_f32 v1, v2, v3
	flat_store_dwordx2 v[68:69], v[48:49] offset:48
	flat_store_dwordx2 v[68:69], v[32:33] offset:112
	flat_store_dwordx2 v[68:69], v[16:17] offset:176
	flat_store_dwordx2 v[68:69], v[0:1] offset:240

; #define LAS __attribute__((address_space(3)))
; __device__ __forceinline__ f32x4 zero4v() { f32x4 z = (f32x4){0.f, 0.f, 0.f, 0.f}; asm volatile("" : "+v"(z)); return z; }
; __device__ __forceinline__ void na_unit(const Frame& F, int l, int gi, int hp) {
;     ...
;         for (int tl = 0; tl < ntl; ++tl) {
;             const int kbase = win ? c0 : tl * 32;
;             f32x4 s[2];
; #pragma unroll
;             for (int ks = 0; ks < 2; ++ks) {
;                 s[ks] = zero4v();
; #pragma unroll
;                 for (int kk = 0; kk < 2; ++kk) {
;                     const bf16x8 kf = *(const LAS bf16x8*)(kb + krd + (kbase + ks * 16) * NA_KSTR + kk * 64);
;                     s[ks] = __builtin_amdgcn_mfma_f32_16x16x32_bf16(kf, Qf[kk], s[ks], 0, 0, 0);
;                 }
;             }
;             if (win) {
;                 const int dr = (r0 + p) - gi + 7;
; #pragma unroll
;                 for (int ks = 0; ks < 2; ++ks)
; #pragma unroll
;                     for (int j = 0; j < 4; ++j) {
;                         const int cc = c0 + 16 * ks + 4 * g + j, rel = cc - cs_;
;                         const bool valid = (rel >= 0) && (rel < 16);
;                         const int bi = min(max(cc - qc + 15, 0), 30);
;                         const float bias = rpb[dr * 31 + bi];
;                         s[ks][j] = valid ? (s[ks][j] * SC + bias) : NEG_BIG;
;                     }
;     ...
;                 const LAS unsigned char* vp = vb + vrd + kbase * NA_VSTR + dt * 32;
;                 const bf16x8 vf = tr_pair(vp, vp + 16 * NA_VSTR);
.LBB0_989:
	s_cmp_gt_u32 s46, 7
	s_cselect_b64 s[44:45], -1, 0
	s_or_b64 s[44:45], s[38:39], s[44:45]
	s_mul_i32 s91, s80, 0x4800
	s_and_b64 vcc, s[44:45], exec
	v_add_u32_e32 v78, s91, v47
	s_cselect_b32 s89, 0, s70
	v_add_u32_e32 v36, s89, v78
	ds_read_b128 v[4:7], v36
	ds_read_b128 v[156:159], v36 offset:4608
	ds_read_b128 v[152:155], v36 offset:64
	ds_read_b128 v[160:163], v36 offset:4672
	v_add_u32_e32 v211, s91, v50
	v_add_u32_e32 v211, s89, v211
	ds_read_b64_tr_b16 v[230:231], v211 offset:55296
	ds_read_b64_tr_b16 v[232:233], v211 offset:59904
	ds_read_b64_tr_b16 v[234:235], v211 offset:55360
	ds_read_b64_tr_b16 v[236:237], v211 offset:59968
	ds_read_b64_tr_b16 v[238:239], v211 offset:55328
	ds_read_b64_tr_b16 v[240:241], v211 offset:59936
	ds_read_b64_tr_b16 v[242:243], v211 offset:55392
	ds_read_b64_tr_b16 v[244:245], v211 offset:60000
	s_mov_b64 s[46:47], -1
	s_cbranch_vccnz .Lmy_na_nobias
	v_add_u32_e32 v202, s76, v76
	v_add_u32_e32 v203, s76, v75
	v_add_u32_e32 v204, s76, v74
	v_add_u32_e32 v205, s76, v73
	v_add_u32_e32 v206, s76, v72
	v_add_u32_e32 v207, s76, v71
	v_add_u32_e32 v208, s76, v70
	v_add_u32_e32 v209, s76, v69
	ds_read_b32 v184, v202
	ds_read_b32 v185, v203
	ds_read_b32 v186, v204
	ds_read_b32 v187, v205
	ds_read_b32 v188, v206
	ds_read_b32 v189, v207
	ds_read_b32 v190, v208
	ds_read_b32 v191, v209
.Lmy_na_nobias:
	s_waitcnt lgkmcnt(11)
	v_mfma_f32_16x16x32_bf16 v[0:3], v[4:7], v[8:11], v[132:135]
	s_waitcnt lgkmcnt(10)
	v_mfma_f32_16x16x32_bf16 v[164:167], v[156:159], v[8:11], v[132:135]
	s_waitcnt lgkmcnt(9)
	v_mfma_f32_16x16x32_bf16 v[32:35], v[152:155], v[12:15], v[0:3]
	s_waitcnt lgkmcnt(8)
	v_mfma_f32_16x16x32_bf16 v[36:39], v[160:163], v[12:15], v[164:167]
	s_cbranch_vccnz .LBB0_1007
	s_waitcnt lgkmcnt(0)
	v_mov_b32_e32 v210, 0xf149f2ca
	s_nop 5
	v_fmac_f32_e32 v184, 0x3e38aa3b, v32
	v_fmac_f32_e32 v185, 0x3e38aa3b, v33
	v_fmac_f32_e32 v186, 0x3e38aa3b, v34
	v_fmac_f32_e32 v187, 0x3e38aa3b, v35
	v_fmac_f32_e32 v188, 0x3e38aa3b, v36
	v_fmac_f32_e32 v189, 0x3e38aa3b, v37
	v_fmac_f32_e32 v190, 0x3e38aa3b, v38
	v_fmac_f32_e32 v191, 0x3e38aa3b, v39
	v_cndmask_b32_e64 v0, v210, v184, s[12:13]
	v_cndmask_b32_e64 v1, v210, v185, s[14:15]
	v_cndmask_b32_e64 v2, v210, v186, s[16:17]
	v_cndmask_b32_e64 v3, v210, v187, s[18:19]
	v_cndmask_b32_e64 v4, v210, v188, s[20:21]
	v_cndmask_b32_e64 v5, v210, v189, s[22:23]
	v_cndmask_b32_e64 v6, v210, v190, s[24:25]
	v_cndmask_b32_e64 v7, v210, v191, s[26:27]
	s_mov_b64 s[46:47], 0

; #define LAS __attribute__((address_space(3)))
; __device__ __forceinline__ void na_unit(const Frame& F, int l, int gi, int hp) {
;     ...
;             float alpha; sm_update<2>(s, m, lsum, alpha, F.lane, 1.0f);
; #pragma unroll
;             for (int dt = 0; dt < 4; ++dt) O[dt] = O[dt] * alpha;
;             const bf16x8 P = pack_p(s[0], s[1]);
; #pragma unroll
;             for (int dt = 0; dt < 4; ++dt) {
;                 const LAS unsigned char* vp = vb + vrd + kbase * NA_VSTR + dt * 32;
;                 const bf16x8 vf = tr_pair(vp, vp + 16 * NA_VSTR);
;                 O[dt] = __builtin_amdgcn_mfma_f32_16x16x32_bf16(vf, P, O[dt], 0, 0, 0);
;             }
.LBB0_1009:
	s_nop 1
	v_max_f32_e32 v32, v3, v3
	v_max_f32_e32 v34, v2, v2
	v_max_f32_e32 v32, v34, v32
	v_max3_f32 v32, v0, v1, v32
	v_max3_f32 v34, v5, v6, v7
	v_max3_f32 v32, v32, v4, v34
	v_mov_b32_e32 v34, v32
	s_nop 1
	v_permlane16_swap_b32_e32 v32, v34
	v_max_f32_e32 v34, v34, v34
	v_max_f32_e32 v32, v32, v32
	v_max_f32_e32 v32, v32, v34
	v_mov_b32_e32 v34, v32
	s_nop 1
	v_permlane32_swap_b32_e32 v32, v34
	v_max3_f32 v32, v79, v32, v34
	v_sub_f32_e32 v34, v79, v32
	v_sub_f32_e32 v0, v0, v32
	v_exp_f32_e32 v38, v34
	v_exp_f32_e32 v34, v0
	v_sub_f32_e32 v0, v1, v32
	v_exp_f32_e32 v35, v0
	v_sub_f32_e32 v0, v2, v32
	v_exp_f32_e32 v36, v0
	v_sub_f32_e32 v0, v3, v32
	v_exp_f32_e32 v37, v0
	v_sub_f32_e32 v0, v4, v32
	v_exp_f32_e32 v39, v0
	v_sub_f32_e32 v0, v5, v32
	v_exp_f32_e32 v79, v0
	v_sub_f32_e32 v0, v6, v32
	v_pk_mul_f32 v[4:5], v[20:21], v[38:39] op_sel_hi:[1,0]
	v_add_f32_e32 v20, 0, v34
	v_exp_f32_e32 v80, v0
	v_sub_f32_e32 v0, v7, v32
	v_add_f32_e32 v20, v35, v20
	v_exp_f32_e32 v84, v0
	v_add_f32_e32 v20, v36, v20
	v_add_f32_e32 v20, v37, v20
	v_add_u32_e32 v33, s91, v50
	v_add_f32_e32 v20, v39, v20
	v_pk_mul_f32 v[2:3], v[26:27], v[38:39] op_sel_hi:[1,0]
	v_pk_mul_f32 v[0:1], v[24:25], v[38:39] op_sel_hi:[1,0]
	v_pk_mul_f32 v[6:7], v[22:23], v[38:39] op_sel_hi:[1,0]
	v_pk_mul_f32 v[18:19], v[18:19], v[38:39] op_sel_hi:[1,0]
	v_pk_mul_f32 v[16:17], v[16:17], v[38:39] op_sel_hi:[1,0]
	v_pk_mul_f32 v[30:31], v[30:31], v[38:39] op_sel_hi:[1,0]
	v_pk_mul_f32 v[28:29], v[28:29], v[38:39] op_sel_hi:[1,0]
	v_add_f32_e32 v20, v79, v20
	v_cvt_pk_bf16_f32 v34, v34, v35
	v_cvt_pk_bf16_f32 v35, v36, v37
	v_cvt_pk_bf16_f32 v36, v39, v79
	v_add_u32_e32 v39, s89, v33
	v_add_f32_e32 v85, v80, v20
	v_cvt_pk_bf16_f32 v37, v80, v84
	s_and_b64 vcc, s[44:45], exec
	s_waitcnt lgkmcnt(0)
	s_nop 0
	v_mfma_f32_16x16x32_bf16 v[24:27], v[230:233], v[34:37], v[0:3]
	v_mfma_f32_16x16x32_bf16 v[16:19], v[234:237], v[34:37], v[16:19]
	v_mfma_f32_16x16x32_bf16 v[20:23], v[238:241], v[34:37], v[4:7]
	v_mfma_f32_16x16x32_bf16 v[28:31], v[242:245], v[34:37], v[28:31]
	v_add_f32_e32 v0, v84, v85
	v_fmac_f32_e32 v0, v77, v38
	s_cbranch_vccnz .LBB0_1012
	s_mov_b64 s[44:45], -1
	s_and_b64 vcc, exec, s[42:43]
	s_cbranch_vccnz .LBB0_1013
